# residual epilogues store X write-through (sc1) so the panel release fence has little to flush
# baseline (speedup 1.0000x reference)
.LBB0_1241:
	ds_read_b128 v[142:145], v155
	ds_read_b128 v[146:149], v155 offset:1024
	ds_read_b128 v[158:161], v155 offset:2048
	ds_read_b128 v[162:165], v155 offset:3072
	s_add_u32 s33, s36, 0xfffc0080
	s_addc_u32 s40, s37, -1
	s_cmp_eq_u32 s81, 12
	s_cselect_b32 s53, s29, s40
	s_cselect_b32 s52, s77, s33
	s_cselect_b32 s41, s27, s80
	s_cselect_b32 s40, s78, s79
	v_lshl_add_u64 v[150:151], s[36:37], 0, v[136:137]
	s_add_i32 m0, s58, 0xc000
	ds_read_b128 v[166:169], v156
	ds_read_b128 v[178:181], v156 offset:1024
	ds_read_b128 v[182:185], v156 offset:2048
	ds_read_b128 v[186:189], v156 offset:3072
	ds_read_b128 v[190:193], v156 offset:4096
	ds_read_b128 v[194:197], v156 offset:5120
	ds_read_b128 v[198:201], v156 offset:6144
	ds_read_b128 v[202:205], v156 offset:7168
	global_load_lds_dwordx4 v[150:151], off
	v_lshl_add_u64 v[150:151], s[36:37], 0, v[134:135]
	s_add_i32 m0, s58, 0xe000
	s_nop 0
	global_load_lds_dwordx4 v[150:151], off
	s_waitcnt lgkmcnt(8)
	s_barrier
	s_waitcnt lgkmcnt(0)
	s_setprio 1
	s_waitcnt lgkmcnt(0)
	v_mfma_f32_16x16x32_bf16 v[124:127], v[142:145], v[166:169], v[124:127]
	v_mfma_f32_16x16x32_bf16 v[120:123], v[158:161], v[166:169], v[120:123]
	v_mfma_f32_16x16x32_bf16 v[116:119], v[142:145], v[182:185], v[116:119]
	v_mfma_f32_16x16x32_bf16 v[112:115], v[158:161], v[182:185], v[112:115]
	v_mfma_f32_16x16x32_bf16 v[108:111], v[142:145], v[190:193], v[108:111]
	v_mfma_f32_16x16x32_bf16 v[104:107], v[158:161], v[190:193], v[104:107]
	v_mfma_f32_16x16x32_bf16 v[100:103], v[142:145], v[198:201], v[100:103]
	v_mfma_f32_16x16x32_bf16 v[96:99], v[158:161], v[198:201], v[96:99]
	v_mfma_f32_16x16x32_bf16 v[124:127], v[146:149], v[178:181], v[124:127]
	v_mfma_f32_16x16x32_bf16 v[120:123], v[162:165], v[178:181], v[120:123]
	v_mfma_f32_16x16x32_bf16 v[116:119], v[146:149], v[186:189], v[116:119]
	v_mfma_f32_16x16x32_bf16 v[112:115], v[162:165], v[186:189], v[112:115]
	v_mfma_f32_16x16x32_bf16 v[108:111], v[146:149], v[194:197], v[108:111]
	v_mfma_f32_16x16x32_bf16 v[104:107], v[162:165], v[194:197], v[104:107]
	v_mfma_f32_16x16x32_bf16 v[100:103], v[146:149], v[202:205], v[100:103]
	v_mfma_f32_16x16x32_bf16 v[96:99], v[162:165], v[202:205], v[96:99]
	s_setprio 0
	s_barrier
	s_add_i32 s33, s68, s57
	v_lshl_add_u64 v[150:151], s[40:41], 0, v[130:131]
	s_mov_b32 m0, s33
	ds_read_b128 v[206:209], v157
	ds_read_b128 v[210:213], v157 offset:1024
	ds_read_b128 v[214:217], v157 offset:2048
	ds_read_b128 v[218:221], v157 offset:3072
	global_load_lds_dwordx4 v[150:151], off
	v_lshl_add_u64 v[222:223], s[40:41], 0, v[128:129]
	s_add_i32 m0, s33, 0x2000
	s_nop 0
	global_load_lds_dwordx4 v[222:223], off
	s_barrier
	s_waitcnt lgkmcnt(0)
	s_setprio 1
	s_waitcnt lgkmcnt(0)
	v_mfma_f32_16x16x32_bf16 v[92:95], v[206:209], v[166:169], v[92:95]
	v_mfma_f32_16x16x32_bf16 v[88:91], v[214:217], v[166:169], v[88:91]
	v_mfma_f32_16x16x32_bf16 v[84:87], v[206:209], v[182:185], v[84:87]
	v_mfma_f32_16x16x32_bf16 v[80:83], v[214:217], v[182:185], v[80:83]
	v_mfma_f32_16x16x32_bf16 v[76:79], v[206:209], v[190:193], v[76:79]
	v_mfma_f32_16x16x32_bf16 v[72:75], v[214:217], v[190:193], v[72:75]
	v_mfma_f32_16x16x32_bf16 v[68:71], v[206:209], v[198:201], v[68:71]
	v_mfma_f32_16x16x32_bf16 v[64:67], v[214:217], v[198:201], v[64:67]
	v_mfma_f32_16x16x32_bf16 v[92:95], v[210:213], v[178:181], v[92:95]
	v_mfma_f32_16x16x32_bf16 v[88:91], v[218:221], v[178:181], v[88:91]
	v_mfma_f32_16x16x32_bf16 v[84:87], v[210:213], v[186:189], v[84:87]
	v_mfma_f32_16x16x32_bf16 v[80:83], v[218:221], v[186:189], v[80:83]
	v_mfma_f32_16x16x32_bf16 v[76:79], v[210:213], v[194:197], v[76:79]
	v_mfma_f32_16x16x32_bf16 v[72:75], v[218:221], v[194:197], v[72:75]
	v_mfma_f32_16x16x32_bf16 v[68:71], v[210:213], v[202:205], v[68:71]
	v_mfma_f32_16x16x32_bf16 v[64:67], v[218:221], v[202:205], v[64:67]
	s_setprio 0
	s_mov_b32 m0, s58
	v_lshl_add_u64 v[224:225], s[52:53], 0, v[130:131]
	s_barrier
	ds_read_b128 v[166:169], v156 offset:16384
	ds_read_b128 v[178:181], v156 offset:17408
	ds_read_b128 v[182:185], v156 offset:18432
	ds_read_b128 v[186:189], v156 offset:19456
	ds_read_b128 v[190:193], v156 offset:20480
	ds_read_b128 v[194:197], v156 offset:21504
	ds_read_b128 v[198:201], v156 offset:22528
	ds_read_b128 v[202:205], v156 offset:23552
	global_load_lds_dwordx4 v[224:225], off
	v_lshl_add_u64 v[226:227], s[52:53], 0, v[128:129]
	s_mov_b32 m0, s59
	s_nop 0
	global_load_lds_dwordx4 v[226:227], off
	s_barrier
	s_waitcnt lgkmcnt(0)
	s_setprio 1
	s_waitcnt lgkmcnt(0)
	v_mfma_f32_16x16x32_bf16 v[60:63], v[142:145], v[166:169], v[60:63]
	v_mfma_f32_16x16x32_bf16 v[56:59], v[158:161], v[166:169], v[56:59]
	v_mfma_f32_16x16x32_bf16 v[52:55], v[142:145], v[182:185], v[52:55]
	v_mfma_f32_16x16x32_bf16 v[48:51], v[158:161], v[182:185], v[48:51]
	v_mfma_f32_16x16x32_bf16 v[44:47], v[142:145], v[190:193], v[44:47]
	v_mfma_f32_16x16x32_bf16 v[40:43], v[158:161], v[190:193], v[40:43]
	v_mfma_f32_16x16x32_bf16 v[36:39], v[142:145], v[198:201], v[36:39]
	v_mfma_f32_16x16x32_bf16 v[32:35], v[158:161], v[198:201], v[32:35]
	v_mfma_f32_16x16x32_bf16 v[60:63], v[146:149], v[178:181], v[60:63]
	v_mfma_f32_16x16x32_bf16 v[56:59], v[162:165], v[178:181], v[56:59]
	v_mfma_f32_16x16x32_bf16 v[52:55], v[146:149], v[186:189], v[52:55]
	v_mfma_f32_16x16x32_bf16 v[48:51], v[162:165], v[186:189], v[48:51]
	v_mfma_f32_16x16x32_bf16 v[44:47], v[146:149], v[194:197], v[44:47]
	v_mfma_f32_16x16x32_bf16 v[40:43], v[162:165], v[194:197], v[40:43]
	v_mfma_f32_16x16x32_bf16 v[36:39], v[146:149], v[202:205], v[36:39]
	v_mfma_f32_16x16x32_bf16 v[32:35], v[162:165], v[202:205], v[32:35]
	s_setprio 0
	s_barrier
	s_add_u32 s82, s40, 0x40000
	s_addc_u32 s83, s41, 0
	s_add_i32 s33, s69, s57
	v_lshl_add_u64 v[142:143], s[82:83], 0, v[130:131]
	s_mov_b32 m0, s33
	s_nop 0
	global_load_lds_dwordx4 v[142:143], off
	v_lshl_add_u64 v[142:143], s[82:83], 0, v[128:129]
	s_add_i32 m0, s33, 0x2000
	s_nop 0
	global_load_lds_dwordx4 v[142:143], off
	s_waitcnt vmcnt(6)
	s_barrier
	s_setprio 1
	v_mfma_f32_16x16x32_bf16 v[28:31], v[206:209], v[166:169], v[28:31]
	v_mfma_f32_16x16x32_bf16 v[24:27], v[214:217], v[166:169], v[24:27]
	v_mfma_f32_16x16x32_bf16 v[20:23], v[206:209], v[182:185], v[20:23]
	v_mfma_f32_16x16x32_bf16 v[16:19], v[214:217], v[182:185], v[16:19]
	v_mfma_f32_16x16x32_bf16 v[12:15], v[206:209], v[190:193], v[12:15]
	v_mfma_f32_16x16x32_bf16 v[8:11], v[214:217], v[190:193], v[8:11]
	v_mfma_f32_16x16x32_bf16 v[4:7], v[206:209], v[198:201], v[4:7]
	v_mfma_f32_16x16x32_bf16 v[0:3], v[214:217], v[198:201], v[0:3]
	v_mfma_f32_16x16x32_bf16 v[28:31], v[210:213], v[178:181], v[28:31]
	v_mfma_f32_16x16x32_bf16 v[24:27], v[218:221], v[178:181], v[24:27]
	v_mfma_f32_16x16x32_bf16 v[20:23], v[210:213], v[186:189], v[20:23]
	v_mfma_f32_16x16x32_bf16 v[16:19], v[218:221], v[186:189], v[16:19]
	v_mfma_f32_16x16x32_bf16 v[12:15], v[210:213], v[194:197], v[12:15]
	v_mfma_f32_16x16x32_bf16 v[8:11], v[218:221], v[194:197], v[8:11]
	v_mfma_f32_16x16x32_bf16 v[4:7], v[210:213], v[202:205], v[4:7]
	v_mfma_f32_16x16x32_bf16 v[0:3], v[218:221], v[202:205], v[0:3]
	s_setprio 0
	s_add_i32 s33, 0, 0x18000
	v_add_u32_e32 v132, s33, v153
	s_barrier
	ds_read_b128 v[142:145], v132
	ds_read_b128 v[146:149], v132 offset:1024
	ds_read_b128 v[158:161], v132 offset:2048
	ds_read_b128 v[162:165], v132 offset:3072
	s_add_u32 s52, s52, 0x40000
	s_addc_u32 s53, s53, 0
	s_mov_b32 m0, s60
	v_lshl_add_u64 v[206:207], s[52:53], 0, v[130:131]
	ds_read_b128 v[166:169], v156 offset:32768
	ds_read_b128 v[178:181], v156 offset:33792
	ds_read_b128 v[182:185], v156 offset:34816
	ds_read_b128 v[186:189], v156 offset:35840
	ds_read_b128 v[190:193], v156 offset:36864
	ds_read_b128 v[194:197], v156 offset:37888
	ds_read_b128 v[198:201], v156 offset:38912
	ds_read_b128 v[202:205], v156 offset:39936
	global_load_lds_dwordx4 v[206:207], off
	v_lshl_add_u64 v[206:207], s[52:53], 0, v[128:129]
	s_mov_b32 m0, s61
	s_nop 0
	global_load_lds_dwordx4 v[206:207], off
	s_waitcnt lgkmcnt(8)
	s_barrier
	s_waitcnt lgkmcnt(0)
	s_setprio 1
	s_waitcnt lgkmcnt(0)
	v_mfma_f32_16x16x32_bf16 v[124:127], v[142:145], v[166:169], v[124:127]
	v_mfma_f32_16x16x32_bf16 v[120:123], v[158:161], v[166:169], v[120:123]
	v_mfma_f32_16x16x32_bf16 v[116:119], v[142:145], v[182:185], v[116:119]
	v_mfma_f32_16x16x32_bf16 v[112:115], v[158:161], v[182:185], v[112:115]
	v_mfma_f32_16x16x32_bf16 v[108:111], v[142:145], v[190:193], v[108:111]
	v_mfma_f32_16x16x32_bf16 v[104:107], v[158:161], v[190:193], v[104:107]
	v_mfma_f32_16x16x32_bf16 v[100:103], v[142:145], v[198:201], v[100:103]
	v_mfma_f32_16x16x32_bf16 v[96:99], v[158:161], v[198:201], v[96:99]
	v_mfma_f32_16x16x32_bf16 v[124:127], v[146:149], v[178:181], v[124:127]
	v_mfma_f32_16x16x32_bf16 v[120:123], v[162:165], v[178:181], v[120:123]
	v_mfma_f32_16x16x32_bf16 v[116:119], v[146:149], v[186:189], v[116:119]
	v_mfma_f32_16x16x32_bf16 v[112:115], v[162:165], v[186:189], v[112:115]
	v_mfma_f32_16x16x32_bf16 v[108:111], v[146:149], v[194:197], v[108:111]
	v_mfma_f32_16x16x32_bf16 v[104:107], v[162:165], v[194:197], v[104:107]
	v_mfma_f32_16x16x32_bf16 v[100:103], v[146:149], v[202:205], v[100:103]
	v_mfma_f32_16x16x32_bf16 v[96:99], v[162:165], v[202:205], v[96:99]
	s_setprio 0
	s_barrier
	s_add_i32 s52, 0, 0x1c000
	s_add_i32 s33, s33, s57
	v_add_u32_e32 v132, s52, v153
	v_lshl_add_u64 v[150:151], v[150:151], 0, s[16:17]
	s_mov_b32 m0, s33
	ds_read_b128 v[206:209], v132
	ds_read_b128 v[210:213], v132 offset:1024
	ds_read_b128 v[214:217], v132 offset:2048
	ds_read_b128 v[218:221], v132 offset:3072
	global_load_lds_dwordx4 v[150:151], off
	v_lshl_add_u64 v[150:151], v[222:223], 0, s[16:17]
	s_add_i32 m0, s33, 0x2000
	s_nop 0
	global_load_lds_dwordx4 v[150:151], off
	s_barrier
	s_waitcnt lgkmcnt(0)
	s_setprio 1
	s_waitcnt lgkmcnt(0)
	v_mfma_f32_16x16x32_bf16 v[92:95], v[206:209], v[166:169], v[92:95]
	v_mfma_f32_16x16x32_bf16 v[88:91], v[214:217], v[166:169], v[88:91]
	v_mfma_f32_16x16x32_bf16 v[84:87], v[206:209], v[182:185], v[84:87]
	v_mfma_f32_16x16x32_bf16 v[80:83], v[214:217], v[182:185], v[80:83]
	v_mfma_f32_16x16x32_bf16 v[76:79], v[206:209], v[190:193], v[76:79]
	v_mfma_f32_16x16x32_bf16 v[72:75], v[214:217], v[190:193], v[72:75]
	v_mfma_f32_16x16x32_bf16 v[68:71], v[206:209], v[198:201], v[68:71]
	v_mfma_f32_16x16x32_bf16 v[64:67], v[214:217], v[198:201], v[64:67]
	v_mfma_f32_16x16x32_bf16 v[92:95], v[210:213], v[178:181], v[92:95]
	v_mfma_f32_16x16x32_bf16 v[88:91], v[218:221], v[178:181], v[88:91]
	v_mfma_f32_16x16x32_bf16 v[84:87], v[210:213], v[186:189], v[84:87]
	v_mfma_f32_16x16x32_bf16 v[80:83], v[218:221], v[186:189], v[80:83]
	v_mfma_f32_16x16x32_bf16 v[76:79], v[210:213], v[194:197], v[76:79]
	v_mfma_f32_16x16x32_bf16 v[72:75], v[218:221], v[194:197], v[72:75]
	v_mfma_f32_16x16x32_bf16 v[68:71], v[210:213], v[202:205], v[68:71]
	v_mfma_f32_16x16x32_bf16 v[64:67], v[218:221], v[202:205], v[64:67]
	s_setprio 0
	s_mov_b32 m0, s62
	v_lshl_add_u64 v[150:151], v[224:225], 0, s[16:17]
	s_barrier
	ds_read_b128 v[166:169], v156 offset:49152
	ds_read_b128 v[178:181], v156 offset:50176
	ds_read_b128 v[182:185], v156 offset:51200
	ds_read_b128 v[186:189], v156 offset:52224
	ds_read_b128 v[190:193], v156 offset:53248
	ds_read_b128 v[194:197], v156 offset:54272
	ds_read_b128 v[198:201], v156 offset:55296
	ds_read_b128 v[202:205], v156 offset:56320
	global_load_lds_dwordx4 v[150:151], off
	v_lshl_add_u64 v[150:151], v[226:227], 0, s[16:17]
	s_mov_b32 m0, s63
	s_nop 0
	global_load_lds_dwordx4 v[150:151], off
	s_barrier
	s_waitcnt lgkmcnt(0)
	s_setprio 1
	s_waitcnt lgkmcnt(0)
	v_mfma_f32_16x16x32_bf16 v[60:63], v[142:145], v[166:169], v[60:63]
	v_mfma_f32_16x16x32_bf16 v[56:59], v[158:161], v[166:169], v[56:59]
	v_mfma_f32_16x16x32_bf16 v[52:55], v[142:145], v[182:185], v[52:55]
	v_mfma_f32_16x16x32_bf16 v[48:51], v[158:161], v[182:185], v[48:51]
	v_mfma_f32_16x16x32_bf16 v[44:47], v[142:145], v[190:193], v[44:47]
	v_mfma_f32_16x16x32_bf16 v[40:43], v[158:161], v[190:193], v[40:43]
	v_mfma_f32_16x16x32_bf16 v[36:39], v[142:145], v[198:201], v[36:39]
	v_mfma_f32_16x16x32_bf16 v[32:35], v[158:161], v[198:201], v[32:35]
	v_mfma_f32_16x16x32_bf16 v[60:63], v[146:149], v[178:181], v[60:63]
	v_mfma_f32_16x16x32_bf16 v[56:59], v[162:165], v[178:181], v[56:59]
	v_mfma_f32_16x16x32_bf16 v[52:55], v[146:149], v[186:189], v[52:55]
	v_mfma_f32_16x16x32_bf16 v[48:51], v[162:165], v[186:189], v[48:51]
	v_mfma_f32_16x16x32_bf16 v[44:47], v[146:149], v[194:197], v[44:47]
	v_mfma_f32_16x16x32_bf16 v[40:43], v[162:165], v[194:197], v[40:43]
	v_mfma_f32_16x16x32_bf16 v[36:39], v[146:149], v[202:205], v[36:39]
	v_mfma_f32_16x16x32_bf16 v[32:35], v[162:165], v[202:205], v[32:35]
	s_setprio 0
	s_barrier
	s_add_u32 s40, s40, 0x40080
	s_addc_u32 s41, s41, 0
	s_add_i32 s33, s52, s57
	v_lshl_add_u64 v[142:143], s[40:41], 0, v[130:131]
	s_mov_b32 m0, s33
	s_nop 0
	global_load_lds_dwordx4 v[142:143], off
	v_lshl_add_u64 v[142:143], s[40:41], 0, v[128:129]
	s_add_i32 m0, s33, 0x2000
	s_nop 0
	global_load_lds_dwordx4 v[142:143], off
	s_waitcnt vmcnt(6)
	s_barrier
	s_setprio 1
	v_mfma_f32_16x16x32_bf16 v[28:31], v[206:209], v[166:169], v[28:31]
	v_mfma_f32_16x16x32_bf16 v[24:27], v[214:217], v[166:169], v[24:27]
	v_mfma_f32_16x16x32_bf16 v[20:23], v[206:209], v[182:185], v[20:23]
	v_mfma_f32_16x16x32_bf16 v[16:19], v[214:217], v[182:185], v[16:19]
	v_mfma_f32_16x16x32_bf16 v[12:15], v[206:209], v[190:193], v[12:15]
	v_mfma_f32_16x16x32_bf16 v[8:11], v[214:217], v[190:193], v[8:11]
	v_mfma_f32_16x16x32_bf16 v[4:7], v[206:209], v[198:201], v[4:7]
	v_mfma_f32_16x16x32_bf16 v[0:3], v[214:217], v[198:201], v[0:3]
	v_mfma_f32_16x16x32_bf16 v[28:31], v[210:213], v[178:181], v[28:31]
	v_mfma_f32_16x16x32_bf16 v[24:27], v[218:221], v[178:181], v[24:27]
	v_mfma_f32_16x16x32_bf16 v[20:23], v[210:213], v[186:189], v[20:23]
	v_mfma_f32_16x16x32_bf16 v[16:19], v[218:221], v[186:189], v[16:19]
	v_mfma_f32_16x16x32_bf16 v[12:15], v[210:213], v[194:197], v[12:15]
	v_mfma_f32_16x16x32_bf16 v[8:11], v[218:221], v[194:197], v[8:11]
	v_mfma_f32_16x16x32_bf16 v[4:7], v[210:213], v[202:205], v[4:7]
	v_mfma_f32_16x16x32_bf16 v[0:3], v[218:221], v[202:205], v[0:3]
	s_setprio 0
	s_add_i32 s81, s81, 2
	s_add_u32 s79, s79, 0x100
	s_addc_u32 s80, s80, 0
	s_add_u32 s36, s36, 0x100
	s_addc_u32 s37, s37, 0
	s_cmp_gt_u32 s81, 13
	s_barrier
	s_cbranch_scc0 .LBB0_1241
	s_load_dwordx4 s[80:83], s[6:7], 0x0
	s_lshl_b32 s77, s10, 8
	v_lshl_or_b32 v142, s76, 8, v154
	v_add_u32_e32 v132, s77, v152
	v_lshlrev_b32_e32 v142, 2, v142
	s_sub_u32 s78, s77, 0x1000
	s_lshr_b32 s78, s78, 11
	s_mul_i32 s78, s78, 6
	s_add_i32 s78, s78, 8
	s_cmp_gt_i32 s10, 15
	s_cselect_b32 s78, s78, 2
	s_cselect_b32 s79, 0x1000000, 0
	s_lshl_b32 s78, s78, 12
	s_add_u32 s48, s66, s78
	s_addc_u32 s49, s67, 0
	v_lshl_add_u32 v143, v132, 12, v142
	global_load_dwordx4 v[144:147], v142, s[48:49]
	global_load_dwordx4 v[148:151], v142, s[48:49] offset:64
	global_load_dwordx4 v[158:161], v142, s[48:49] offset:512
	global_load_dwordx4 v[162:165], v142, s[48:49] offset:576
	s_mov_b64 s[86:87], s[12:13]
	s_cmp_gt_i32 s10, 15
	s_waitcnt lgkmcnt(0)
	s_cselect_b32 s84, s82, s80
	s_cselect_b32 s85, s83, s81
	s_sub_u32 s84, s84, s79
	s_subb_u32 s85, s85, 0
	global_load_dwordx4 v[178:181], v143, s[84:85]
	global_load_dwordx4 v[182:185], v143, s[84:85] offset:64
	global_load_dwordx4 v[186:189], v143, s[84:85] offset:512
	global_load_dwordx4 v[190:193], v143, s[84:85] offset:576
	s_add_u32 s84, s84, 0x10000
	s_addc_u32 s85, s85, 0
	global_load_dwordx4 v[194:197], v143, s[84:85]
	global_load_dwordx4 v[198:201], v143, s[84:85] offset:64
	global_load_dwordx4 v[202:205], v143, s[84:85] offset:512
	global_load_dwordx4 v[206:209], v143, s[84:85] offset:576
	s_add_u32 s84, s84, 0x10000
	s_addc_u32 s85, s85, 0
	global_load_dwordx4 v[210:213], v143, s[84:85]
	global_load_dwordx4 v[214:217], v143, s[84:85] offset:64
	global_load_dwordx4 v[218:221], v143, s[84:85] offset:512
	global_load_dwordx4 v[222:225], v143, s[84:85] offset:576
	s_add_u32 s84, s84, 0x10000
	s_addc_u32 s85, s85, 0
	global_load_dwordx4 v[226:229], v143, s[84:85]
	global_load_dwordx4 v[230:233], v143, s[84:85] offset:64
	s_waitcnt vmcnt(13)
	v_pk_fma_f32 v[124:125], v[124:125], v[144:145], v[178:179]
	v_pk_fma_f32 v[126:127], v[126:127], v[146:147], v[180:181]
	global_store_dwordx4 v143, v[124:127], s[86:87] sc1
	global_load_dwordx4 v[178:181], v143, s[84:85] offset:512
	s_waitcnt vmcnt(14)
	v_pk_fma_f32 v[120:121], v[120:121], v[148:149], v[182:183]
	v_pk_fma_f32 v[122:123], v[122:123], v[150:151], v[184:185]
	global_store_dwordx4 v143, v[120:123], s[86:87] offset:64 sc1
	global_load_dwordx4 v[182:185], v143, s[84:85] offset:576
	s_waitcnt vmcnt(15)
	v_pk_fma_f32 v[92:93], v[92:93], v[158:159], v[186:187]
	v_pk_fma_f32 v[94:95], v[94:95], v[160:161], v[188:189]
	global_store_dwordx4 v143, v[92:95], s[86:87] offset:512 sc1
	s_add_u32 s84, s84, 0x50000
	s_addc_u32 s85, s85, 0
	global_load_dwordx4 v[186:189], v143, s[84:85]
	s_waitcnt vmcnt(16)
	v_pk_fma_f32 v[88:89], v[88:89], v[162:163], v[190:191]
	v_pk_fma_f32 v[90:91], v[90:91], v[164:165], v[192:193]
	global_store_dwordx4 v143, v[88:91], s[86:87] offset:576 sc1
	global_load_dwordx4 v[190:193], v143, s[84:85] offset:64
	s_add_u32 s86, s86, 0x10000
	s_addc_u32 s87, s87, 0
	s_waitcnt vmcnt(17)
	v_pk_fma_f32 v[116:117], v[116:117], v[144:145], v[194:195]
	v_pk_fma_f32 v[118:119], v[118:119], v[146:147], v[196:197]
	global_store_dwordx4 v143, v[116:119], s[86:87] sc1
	global_load_dwordx4 v[194:197], v143, s[84:85] offset:512
	s_waitcnt vmcnt(18)
	v_pk_fma_f32 v[112:113], v[112:113], v[148:149], v[198:199]
	v_pk_fma_f32 v[114:115], v[114:115], v[150:151], v[200:201]
	global_store_dwordx4 v143, v[112:115], s[86:87] offset:64 sc1
	global_load_dwordx4 v[198:201], v143, s[84:85] offset:576
	s_waitcnt vmcnt(19)
	v_pk_fma_f32 v[84:85], v[84:85], v[158:159], v[202:203]
	v_pk_fma_f32 v[86:87], v[86:87], v[160:161], v[204:205]
	global_store_dwordx4 v143, v[84:87], s[86:87] offset:512 sc1
	s_add_u32 s84, s84, 0x10000
	s_addc_u32 s85, s85, 0
	global_load_dwordx4 v[202:205], v143, s[84:85]
	s_waitcnt vmcnt(20)
	v_pk_fma_f32 v[80:81], v[80:81], v[162:163], v[206:207]
	v_pk_fma_f32 v[82:83], v[82:83], v[164:165], v[208:209]
	global_store_dwordx4 v143, v[80:83], s[86:87] offset:576 sc1
	global_load_dwordx4 v[206:209], v143, s[84:85] offset:64
	s_add_u32 s86, s86, 0x10000
	s_addc_u32 s87, s87, 0
	s_waitcnt vmcnt(21)
	v_pk_fma_f32 v[108:109], v[108:109], v[144:145], v[210:211]
	v_pk_fma_f32 v[110:111], v[110:111], v[146:147], v[212:213]
	global_store_dwordx4 v143, v[108:111], s[86:87] sc1
	global_load_dwordx4 v[210:213], v143, s[84:85] offset:512
	s_waitcnt vmcnt(22)
	v_pk_fma_f32 v[104:105], v[104:105], v[148:149], v[214:215]
	v_pk_fma_f32 v[106:107], v[106:107], v[150:151], v[216:217]
	global_store_dwordx4 v143, v[104:107], s[86:87] offset:64 sc1
	global_load_dwordx4 v[214:217], v143, s[84:85] offset:576
	s_waitcnt vmcnt(23)
	v_pk_fma_f32 v[76:77], v[76:77], v[158:159], v[218:219]
	v_pk_fma_f32 v[78:79], v[78:79], v[160:161], v[220:221]
	global_store_dwordx4 v143, v[76:79], s[86:87] offset:512 sc1
	s_add_u32 s84, s84, 0x10000
	s_addc_u32 s85, s85, 0
	global_load_dwordx4 v[218:221], v143, s[84:85]
	s_waitcnt vmcnt(24)
	v_pk_fma_f32 v[72:73], v[72:73], v[162:163], v[222:223]
	v_pk_fma_f32 v[74:75], v[74:75], v[164:165], v[224:225]
	global_store_dwordx4 v143, v[72:75], s[86:87] offset:576 sc1
	global_load_dwordx4 v[222:225], v143, s[84:85] offset:64
	s_add_u32 s86, s86, 0x10000
	s_addc_u32 s87, s87, 0
	s_waitcnt vmcnt(25)
	v_pk_fma_f32 v[100:101], v[100:101], v[144:145], v[226:227]
	v_pk_fma_f32 v[102:103], v[102:103], v[146:147], v[228:229]
	global_store_dwordx4 v143, v[100:103], s[86:87] sc1
	global_load_dwordx4 v[226:229], v143, s[84:85] offset:512
	s_waitcnt vmcnt(26)
	v_pk_fma_f32 v[96:97], v[96:97], v[148:149], v[230:231]
	v_pk_fma_f32 v[98:99], v[98:99], v[150:151], v[232:233]
	global_store_dwordx4 v143, v[96:99], s[86:87] offset:64 sc1
	global_load_dwordx4 v[230:233], v143, s[84:85] offset:576
	s_waitcnt vmcnt(26)
	v_pk_fma_f32 v[68:69], v[68:69], v[158:159], v[178:179]
	v_pk_fma_f32 v[70:71], v[70:71], v[160:161], v[180:181]
	global_store_dwordx4 v143, v[68:71], s[86:87] offset:512 sc1
	s_add_u32 s84, s84, 0x10000
	s_addc_u32 s85, s85, 0
	global_load_dwordx4 v[178:181], v143, s[84:85]
	s_waitcnt vmcnt(26)
	v_pk_fma_f32 v[64:65], v[64:65], v[162:163], v[182:183]
	v_pk_fma_f32 v[66:67], v[66:67], v[164:165], v[184:185]
	global_store_dwordx4 v143, v[64:67], s[86:87] offset:576 sc1
	global_load_dwordx4 v[182:185], v143, s[84:85] offset:64
	s_add_u32 s86, s86, 0x50000
	s_addc_u32 s87, s87, 0
	s_waitcnt vmcnt(26)
	v_pk_fma_f32 v[60:61], v[60:61], v[144:145], v[186:187]
	v_pk_fma_f32 v[62:63], v[62:63], v[146:147], v[188:189]
	global_store_dwordx4 v143, v[60:63], s[86:87] sc1
	global_load_dwordx4 v[186:189], v143, s[84:85] offset:512
	s_waitcnt vmcnt(26)
	v_pk_fma_f32 v[56:57], v[56:57], v[148:149], v[190:191]
	v_pk_fma_f32 v[58:59], v[58:59], v[150:151], v[192:193]
	global_store_dwordx4 v143, v[56:59], s[86:87] offset:64 sc1
	global_load_dwordx4 v[190:193], v143, s[84:85] offset:576
	s_waitcnt vmcnt(26)
	v_pk_fma_f32 v[28:29], v[28:29], v[158:159], v[194:195]
	v_pk_fma_f32 v[30:31], v[30:31], v[160:161], v[196:197]
	global_store_dwordx4 v143, v[28:31], s[86:87] offset:512 sc1
	s_waitcnt vmcnt(25)
	v_pk_fma_f32 v[24:25], v[24:25], v[162:163], v[198:199]
	v_pk_fma_f32 v[26:27], v[26:27], v[164:165], v[200:201]
	global_store_dwordx4 v143, v[24:27], s[86:87] offset:576 sc1
	s_add_u32 s86, s86, 0x10000
	s_addc_u32 s87, s87, 0
	s_waitcnt vmcnt(24)
	v_pk_fma_f32 v[52:53], v[52:53], v[144:145], v[202:203]
	v_pk_fma_f32 v[54:55], v[54:55], v[146:147], v[204:205]
	global_store_dwordx4 v143, v[52:55], s[86:87] sc1
	s_waitcnt vmcnt(23)
	v_pk_fma_f32 v[48:49], v[48:49], v[148:149], v[206:207]
	v_pk_fma_f32 v[50:51], v[50:51], v[150:151], v[208:209]
	global_store_dwordx4 v143, v[48:51], s[86:87] offset:64 sc1
	s_waitcnt vmcnt(22)
	v_pk_fma_f32 v[20:21], v[20:21], v[158:159], v[210:211]
	v_pk_fma_f32 v[22:23], v[22:23], v[160:161], v[212:213]
	global_store_dwordx4 v143, v[20:23], s[86:87] offset:512 sc1
	s_waitcnt vmcnt(21)
	v_pk_fma_f32 v[16:17], v[16:17], v[162:163], v[214:215]
	v_pk_fma_f32 v[18:19], v[18:19], v[164:165], v[216:217]
	global_store_dwordx4 v143, v[16:19], s[86:87] offset:576 sc1
	s_add_u32 s86, s86, 0x10000
	s_addc_u32 s87, s87, 0
	s_waitcnt vmcnt(20)
	v_pk_fma_f32 v[44:45], v[44:45], v[144:145], v[218:219]
	v_pk_fma_f32 v[46:47], v[46:47], v[146:147], v[220:221]
	global_store_dwordx4 v143, v[44:47], s[86:87] sc1
	s_waitcnt vmcnt(19)
	v_pk_fma_f32 v[40:41], v[40:41], v[148:149], v[222:223]
	v_pk_fma_f32 v[42:43], v[42:43], v[150:151], v[224:225]
	global_store_dwordx4 v143, v[40:43], s[86:87] offset:64 sc1
	s_waitcnt vmcnt(18)
	v_pk_fma_f32 v[12:13], v[12:13], v[158:159], v[226:227]
	v_pk_fma_f32 v[14:15], v[14:15], v[160:161], v[228:229]
	global_store_dwordx4 v143, v[12:15], s[86:87] offset:512 sc1
	s_waitcnt vmcnt(17)
	v_pk_fma_f32 v[8:9], v[8:9], v[162:163], v[230:231]
	v_pk_fma_f32 v[10:11], v[10:11], v[164:165], v[232:233]
	global_store_dwordx4 v143, v[8:11], s[86:87] offset:576 sc1
	s_add_u32 s86, s86, 0x10000
	s_addc_u32 s87, s87, 0
	s_waitcnt vmcnt(16)
	v_pk_fma_f32 v[36:37], v[36:37], v[144:145], v[178:179]
	v_pk_fma_f32 v[38:39], v[38:39], v[146:147], v[180:181]
	global_store_dwordx4 v143, v[36:39], s[86:87] sc1
	s_waitcnt vmcnt(15)
	v_pk_fma_f32 v[32:33], v[32:33], v[148:149], v[182:183]
	v_pk_fma_f32 v[34:35], v[34:35], v[150:151], v[184:185]
	global_store_dwordx4 v143, v[32:35], s[86:87] offset:64 sc1
	s_waitcnt vmcnt(14)
	v_pk_fma_f32 v[4:5], v[4:5], v[158:159], v[186:187]
	v_pk_fma_f32 v[6:7], v[6:7], v[160:161], v[188:189]
	global_store_dwordx4 v143, v[4:7], s[86:87] offset:512 sc1
	s_waitcnt vmcnt(13)
	v_pk_fma_f32 v[0:1], v[0:1], v[162:163], v[190:191]
	v_pk_fma_f32 v[2:3], v[2:3], v[164:165], v[192:193]
	global_store_dwordx4 v143, v[0:3], s[86:87] offset:576 sc1
	s_mov_b32 s76, s26
	s_mov_b64 s[36:37], s[34:35]
	s_mov_b64 s[40:41], s[30:31]
	s_mov_b32 s10, s28
	s_and_b64 vcc, exec, s[4:5]
	s_cbranch_vccz .LBB0_1238
	s_waitcnt vmcnt(0)
	s_cmpk_gt_u32 s45, 0xff
	s_cbranch_scc1 .LBB0_1245
	s_barrier

.LBB0_1460:
	ds_read_b128 v[144:147], v155
	ds_read_b128 v[148:151], v155 offset:1024
	ds_read_b128 v[158:161], v155 offset:2048
	ds_read_b128 v[162:165], v155 offset:3072
	s_add_u32 s33, s52, 0x4000
	s_addc_u32 s54, s53, 0
	s_cmp_eq_u32 s86, 60
	s_cselect_b32 s58, s82, s33
	s_cselect_b32 s59, s37, s54
	s_cselect_b32 s54, s83, s84
	s_cselect_b32 s55, s35, s85
	s_add_u32 s56, s58, 0x8000
	s_addc_u32 s57, s59, 0
	v_lshl_add_u64 v[206:207], s[52:53], 0, v[138:139]
	s_add_i32 m0, s64, 0xc000
	ds_read_b128 v[166:169], v156
	ds_read_b128 v[178:181], v156 offset:1024
	ds_read_b128 v[182:185], v156 offset:2048
	ds_read_b128 v[186:189], v156 offset:3072
	ds_read_b128 v[190:193], v156 offset:4096
	ds_read_b128 v[194:197], v156 offset:5120
	ds_read_b128 v[198:201], v156 offset:6144
	ds_read_b128 v[202:205], v156 offset:7168
	global_load_lds_dwordx4 v[206:207], off
	v_lshl_add_u64 v[206:207], s[52:53], 0, v[136:137]
	s_add_i32 m0, s64, 0xe000
	s_nop 0
	global_load_lds_dwordx4 v[206:207], off
	s_waitcnt lgkmcnt(8)
	s_barrier
	s_waitcnt lgkmcnt(0)
	s_setprio 1
	s_waitcnt lgkmcnt(0)
	v_mfma_f32_16x16x32_bf16 v[124:127], v[144:147], v[166:169], v[124:127]
	v_mfma_f32_16x16x32_bf16 v[120:123], v[158:161], v[166:169], v[120:123]
	v_mfma_f32_16x16x32_bf16 v[108:111], v[144:147], v[182:185], v[108:111]
	v_mfma_f32_16x16x32_bf16 v[104:107], v[158:161], v[182:185], v[104:107]
	v_mfma_f32_16x16x32_bf16 v[92:95], v[144:147], v[190:193], v[92:95]
	v_mfma_f32_16x16x32_bf16 v[88:91], v[158:161], v[190:193], v[88:91]
	v_mfma_f32_16x16x32_bf16 v[76:79], v[144:147], v[198:201], v[76:79]
	v_mfma_f32_16x16x32_bf16 v[72:75], v[158:161], v[198:201], v[72:75]
	v_mfma_f32_16x16x32_bf16 v[124:127], v[148:151], v[178:181], v[124:127]
	v_mfma_f32_16x16x32_bf16 v[120:123], v[162:165], v[178:181], v[120:123]
	v_mfma_f32_16x16x32_bf16 v[108:111], v[148:151], v[186:189], v[108:111]
	v_mfma_f32_16x16x32_bf16 v[104:107], v[162:165], v[186:189], v[104:107]
	v_mfma_f32_16x16x32_bf16 v[92:95], v[148:151], v[194:197], v[92:95]
	v_mfma_f32_16x16x32_bf16 v[88:91], v[162:165], v[194:197], v[88:91]
	v_mfma_f32_16x16x32_bf16 v[76:79], v[148:151], v[202:205], v[76:79]
	v_mfma_f32_16x16x32_bf16 v[72:75], v[162:165], v[202:205], v[72:75]
	s_setprio 0
	s_barrier
	s_add_i32 s33, s74, s63
	v_lshl_add_u64 v[222:223], s[54:55], 0, v[132:133]
	s_mov_b32 m0, s33
	ds_read_b128 v[206:209], v157
	ds_read_b128 v[210:213], v157 offset:1024
	ds_read_b128 v[214:217], v157 offset:2048
	ds_read_b128 v[218:221], v157 offset:3072
	global_load_lds_dwordx4 v[222:223], off
	v_lshl_add_u64 v[224:225], s[54:55], 0, v[128:129]
	s_add_i32 m0, s33, 0x2000
	s_nop 0
	global_load_lds_dwordx4 v[224:225], off
	s_barrier
	s_waitcnt lgkmcnt(0)
	s_setprio 1
	s_waitcnt lgkmcnt(0)
	v_mfma_f32_16x16x32_bf16 v[116:119], v[206:209], v[166:169], v[116:119]
	v_mfma_f32_16x16x32_bf16 v[112:115], v[214:217], v[166:169], v[112:115]
	v_mfma_f32_16x16x32_bf16 v[100:103], v[206:209], v[182:185], v[100:103]
	v_mfma_f32_16x16x32_bf16 v[96:99], v[214:217], v[182:185], v[96:99]
	v_mfma_f32_16x16x32_bf16 v[84:87], v[206:209], v[190:193], v[84:87]
	v_mfma_f32_16x16x32_bf16 v[80:83], v[214:217], v[190:193], v[80:83]
	v_mfma_f32_16x16x32_bf16 v[68:71], v[206:209], v[198:201], v[68:71]
	v_mfma_f32_16x16x32_bf16 v[64:67], v[214:217], v[198:201], v[64:67]
	v_mfma_f32_16x16x32_bf16 v[116:119], v[210:213], v[178:181], v[116:119]
	v_mfma_f32_16x16x32_bf16 v[112:115], v[218:221], v[178:181], v[112:115]
	v_mfma_f32_16x16x32_bf16 v[100:103], v[210:213], v[186:189], v[100:103]
	v_mfma_f32_16x16x32_bf16 v[96:99], v[218:221], v[186:189], v[96:99]
	v_mfma_f32_16x16x32_bf16 v[84:87], v[210:213], v[194:197], v[84:87]
	v_mfma_f32_16x16x32_bf16 v[80:83], v[218:221], v[194:197], v[80:83]
	v_mfma_f32_16x16x32_bf16 v[68:71], v[210:213], v[202:205], v[68:71]
	v_mfma_f32_16x16x32_bf16 v[64:67], v[218:221], v[202:205], v[64:67]
	s_setprio 0
	s_mov_b32 m0, s64
	v_lshl_add_u64 v[226:227], s[58:59], 0, v[134:135]
	s_barrier
	ds_read_b128 v[166:169], v156 offset:16384
	ds_read_b128 v[178:181], v156 offset:17408
	ds_read_b128 v[182:185], v156 offset:18432
	ds_read_b128 v[186:189], v156 offset:19456
	ds_read_b128 v[190:193], v156 offset:20480
	ds_read_b128 v[194:197], v156 offset:21504
	ds_read_b128 v[198:201], v156 offset:22528
	ds_read_b128 v[202:205], v156 offset:23552
	global_load_lds_dwordx4 v[226:227], off
	v_lshl_add_u64 v[226:227], s[58:59], 0, v[130:131]
	s_mov_b32 m0, s65
	s_nop 0
	global_load_lds_dwordx4 v[226:227], off
	s_barrier
	s_waitcnt lgkmcnt(0)
	s_setprio 1
	s_waitcnt lgkmcnt(0)
	v_mfma_f32_16x16x32_bf16 v[60:63], v[144:147], v[166:169], v[60:63]
	v_mfma_f32_16x16x32_bf16 v[56:59], v[158:161], v[166:169], v[56:59]
	v_mfma_f32_16x16x32_bf16 v[44:47], v[144:147], v[182:185], v[44:47]
	v_mfma_f32_16x16x32_bf16 v[40:43], v[158:161], v[182:185], v[40:43]
	v_mfma_f32_16x16x32_bf16 v[28:31], v[144:147], v[190:193], v[28:31]
	v_mfma_f32_16x16x32_bf16 v[24:27], v[158:161], v[190:193], v[24:27]
	v_mfma_f32_16x16x32_bf16 v[12:15], v[144:147], v[198:201], v[12:15]
	v_mfma_f32_16x16x32_bf16 v[8:11], v[158:161], v[198:201], v[8:11]
	v_mfma_f32_16x16x32_bf16 v[60:63], v[148:151], v[178:181], v[60:63]
	v_mfma_f32_16x16x32_bf16 v[56:59], v[162:165], v[178:181], v[56:59]
	v_mfma_f32_16x16x32_bf16 v[44:47], v[148:151], v[186:189], v[44:47]
	v_mfma_f32_16x16x32_bf16 v[40:43], v[162:165], v[186:189], v[40:43]
	v_mfma_f32_16x16x32_bf16 v[28:31], v[148:151], v[194:197], v[28:31]
	v_mfma_f32_16x16x32_bf16 v[24:27], v[162:165], v[194:197], v[24:27]
	v_mfma_f32_16x16x32_bf16 v[12:15], v[148:151], v[202:205], v[12:15]
	v_mfma_f32_16x16x32_bf16 v[8:11], v[162:165], v[202:205], v[8:11]
	s_setprio 0
	s_barrier
	s_add_u32 s88, s54, 0x100000
	s_addc_u32 s89, s55, 0
	s_add_i32 s33, s75, s63
	v_lshl_add_u64 v[144:145], s[88:89], 0, v[132:133]
	s_mov_b32 m0, s33
	s_nop 0
	global_load_lds_dwordx4 v[144:145], off
	v_lshl_add_u64 v[144:145], s[88:89], 0, v[128:129]
	s_add_i32 m0, s33, 0x2000
	s_nop 0
	global_load_lds_dwordx4 v[144:145], off
	s_waitcnt vmcnt(6)
	s_barrier
	s_setprio 1
	v_mfma_f32_16x16x32_bf16 v[52:55], v[206:209], v[166:169], v[52:55]
	v_mfma_f32_16x16x32_bf16 v[48:51], v[214:217], v[166:169], v[48:51]
	v_mfma_f32_16x16x32_bf16 v[36:39], v[206:209], v[182:185], v[36:39]
	v_mfma_f32_16x16x32_bf16 v[32:35], v[214:217], v[182:185], v[32:35]
	v_mfma_f32_16x16x32_bf16 v[20:23], v[206:209], v[190:193], v[20:23]
	v_mfma_f32_16x16x32_bf16 v[16:19], v[214:217], v[190:193], v[16:19]
	v_mfma_f32_16x16x32_bf16 v[4:7], v[206:209], v[198:201], v[4:7]
	v_mfma_f32_16x16x32_bf16 v[0:3], v[214:217], v[198:201], v[0:3]
	v_mfma_f32_16x16x32_bf16 v[52:55], v[210:213], v[178:181], v[52:55]
	v_mfma_f32_16x16x32_bf16 v[48:51], v[218:221], v[178:181], v[48:51]
	v_mfma_f32_16x16x32_bf16 v[36:39], v[210:213], v[186:189], v[36:39]
	v_mfma_f32_16x16x32_bf16 v[32:35], v[218:221], v[186:189], v[32:35]
	v_mfma_f32_16x16x32_bf16 v[20:23], v[210:213], v[194:197], v[20:23]
	v_mfma_f32_16x16x32_bf16 v[16:19], v[218:221], v[194:197], v[16:19]
	v_mfma_f32_16x16x32_bf16 v[4:7], v[210:213], v[202:205], v[4:7]
	v_mfma_f32_16x16x32_bf16 v[0:3], v[218:221], v[202:205], v[0:3]
	s_setprio 0
	s_add_i32 s33, 0, 0x18000
	v_add_u32_e32 v162, s33, v153
	s_barrier
	ds_read_b128 v[144:147], v162
	ds_read_b128 v[148:151], v162 offset:1024
	ds_read_b128 v[158:161], v162 offset:2048
	ds_read_b128 v[162:165], v162 offset:3072
	s_add_u32 s58, s58, 0x4000
	s_addc_u32 s59, s59, 0
	s_mov_b32 m0, s66
	v_lshl_add_u64 v[206:207], s[58:59], 0, v[134:135]
	ds_read_b128 v[166:169], v156 offset:32768
	ds_read_b128 v[178:181], v156 offset:33792
	ds_read_b128 v[182:185], v156 offset:34816
	ds_read_b128 v[186:189], v156 offset:35840
	ds_read_b128 v[190:193], v156 offset:36864
	ds_read_b128 v[194:197], v156 offset:37888
	ds_read_b128 v[198:201], v156 offset:38912
	ds_read_b128 v[202:205], v156 offset:39936
	global_load_lds_dwordx4 v[206:207], off
	v_lshl_add_u64 v[206:207], s[58:59], 0, v[130:131]
	s_mov_b32 m0, s67
	s_nop 0
	global_load_lds_dwordx4 v[206:207], off
	s_waitcnt lgkmcnt(8)
	s_barrier
	s_waitcnt lgkmcnt(0)
	s_setprio 1
	s_waitcnt lgkmcnt(0)
	v_mfma_f32_16x16x32_bf16 v[124:127], v[144:147], v[166:169], v[124:127]
	v_mfma_f32_16x16x32_bf16 v[120:123], v[158:161], v[166:169], v[120:123]
	v_mfma_f32_16x16x32_bf16 v[108:111], v[144:147], v[182:185], v[108:111]
	v_mfma_f32_16x16x32_bf16 v[104:107], v[158:161], v[182:185], v[104:107]
	v_mfma_f32_16x16x32_bf16 v[92:95], v[144:147], v[190:193], v[92:95]
	v_mfma_f32_16x16x32_bf16 v[88:91], v[158:161], v[190:193], v[88:91]
	v_mfma_f32_16x16x32_bf16 v[76:79], v[144:147], v[198:201], v[76:79]
	v_mfma_f32_16x16x32_bf16 v[72:75], v[158:161], v[198:201], v[72:75]
	v_mfma_f32_16x16x32_bf16 v[124:127], v[148:151], v[178:181], v[124:127]
	v_mfma_f32_16x16x32_bf16 v[120:123], v[162:165], v[178:181], v[120:123]
	v_mfma_f32_16x16x32_bf16 v[108:111], v[148:151], v[186:189], v[108:111]
	v_mfma_f32_16x16x32_bf16 v[104:107], v[162:165], v[186:189], v[104:107]
	v_mfma_f32_16x16x32_bf16 v[92:95], v[148:151], v[194:197], v[92:95]
	v_mfma_f32_16x16x32_bf16 v[88:91], v[162:165], v[194:197], v[88:91]
	v_mfma_f32_16x16x32_bf16 v[76:79], v[148:151], v[202:205], v[76:79]
	v_mfma_f32_16x16x32_bf16 v[72:75], v[162:165], v[202:205], v[72:75]
	s_setprio 0
	s_barrier
	s_add_i32 s58, 0, 0x1c000
	s_add_i32 s33, s33, s63
	v_add_u32_e32 v177, s58, v153
	v_lshl_add_u64 v[222:223], v[222:223], 0, s[16:17]
	s_mov_b32 m0, s33
	ds_read_b128 v[206:209], v177
	ds_read_b128 v[210:213], v177 offset:1024
	ds_read_b128 v[214:217], v177 offset:2048
	ds_read_b128 v[218:221], v177 offset:3072
	global_load_lds_dwordx4 v[222:223], off
	v_lshl_add_u64 v[222:223], v[224:225], 0, s[16:17]
	s_add_i32 m0, s33, 0x2000
	s_nop 0
	global_load_lds_dwordx4 v[222:223], off
	s_barrier
	s_waitcnt lgkmcnt(0)
	s_setprio 1
	s_waitcnt lgkmcnt(0)
	v_mfma_f32_16x16x32_bf16 v[116:119], v[206:209], v[166:169], v[116:119]
	v_mfma_f32_16x16x32_bf16 v[112:115], v[214:217], v[166:169], v[112:115]
	v_mfma_f32_16x16x32_bf16 v[100:103], v[206:209], v[182:185], v[100:103]
	v_mfma_f32_16x16x32_bf16 v[96:99], v[214:217], v[182:185], v[96:99]
	v_mfma_f32_16x16x32_bf16 v[84:87], v[206:209], v[190:193], v[84:87]
	v_mfma_f32_16x16x32_bf16 v[80:83], v[214:217], v[190:193], v[80:83]
	v_mfma_f32_16x16x32_bf16 v[68:71], v[206:209], v[198:201], v[68:71]
	v_mfma_f32_16x16x32_bf16 v[64:67], v[214:217], v[198:201], v[64:67]
	v_mfma_f32_16x16x32_bf16 v[116:119], v[210:213], v[178:181], v[116:119]
	v_mfma_f32_16x16x32_bf16 v[112:115], v[218:221], v[178:181], v[112:115]
	v_mfma_f32_16x16x32_bf16 v[100:103], v[210:213], v[186:189], v[100:103]
	v_mfma_f32_16x16x32_bf16 v[96:99], v[218:221], v[186:189], v[96:99]
	v_mfma_f32_16x16x32_bf16 v[84:87], v[210:213], v[194:197], v[84:87]
	v_mfma_f32_16x16x32_bf16 v[80:83], v[218:221], v[194:197], v[80:83]
	v_mfma_f32_16x16x32_bf16 v[68:71], v[210:213], v[202:205], v[68:71]
	v_mfma_f32_16x16x32_bf16 v[64:67], v[218:221], v[202:205], v[64:67]
	s_setprio 0
	s_mov_b32 m0, s68
	v_lshl_add_u64 v[222:223], s[56:57], 0, v[134:135]
	s_barrier
	ds_read_b128 v[166:169], v156 offset:49152
	ds_read_b128 v[178:181], v156 offset:50176
	ds_read_b128 v[182:185], v156 offset:51200
	ds_read_b128 v[186:189], v156 offset:52224
	ds_read_b128 v[190:193], v156 offset:53248
	ds_read_b128 v[194:197], v156 offset:54272
	ds_read_b128 v[198:201], v156 offset:55296
	ds_read_b128 v[202:205], v156 offset:56320
	global_load_lds_dwordx4 v[222:223], off
	v_lshl_add_u64 v[222:223], s[56:57], 0, v[130:131]
	s_mov_b32 m0, s69
	s_nop 0
	global_load_lds_dwordx4 v[222:223], off
	s_barrier
	s_waitcnt lgkmcnt(0)
	s_setprio 1
	s_waitcnt lgkmcnt(0)
	v_mfma_f32_16x16x32_bf16 v[60:63], v[144:147], v[166:169], v[60:63]
	v_mfma_f32_16x16x32_bf16 v[56:59], v[158:161], v[166:169], v[56:59]
	v_mfma_f32_16x16x32_bf16 v[44:47], v[144:147], v[182:185], v[44:47]
	v_mfma_f32_16x16x32_bf16 v[40:43], v[158:161], v[182:185], v[40:43]
	v_mfma_f32_16x16x32_bf16 v[28:31], v[144:147], v[190:193], v[28:31]
	v_mfma_f32_16x16x32_bf16 v[24:27], v[158:161], v[190:193], v[24:27]
	v_mfma_f32_16x16x32_bf16 v[12:15], v[144:147], v[198:201], v[12:15]
	v_mfma_f32_16x16x32_bf16 v[8:11], v[158:161], v[198:201], v[8:11]
	v_mfma_f32_16x16x32_bf16 v[60:63], v[148:151], v[178:181], v[60:63]
	v_mfma_f32_16x16x32_bf16 v[56:59], v[162:165], v[178:181], v[56:59]
	v_mfma_f32_16x16x32_bf16 v[44:47], v[148:151], v[186:189], v[44:47]
	v_mfma_f32_16x16x32_bf16 v[40:43], v[162:165], v[186:189], v[40:43]
	v_mfma_f32_16x16x32_bf16 v[28:31], v[148:151], v[194:197], v[28:31]
	v_mfma_f32_16x16x32_bf16 v[24:27], v[162:165], v[194:197], v[24:27]
	v_mfma_f32_16x16x32_bf16 v[12:15], v[148:151], v[202:205], v[12:15]
	v_mfma_f32_16x16x32_bf16 v[8:11], v[162:165], v[202:205], v[8:11]
	s_setprio 0
	s_barrier
	s_add_u32 s54, s54, 0x100080
	s_addc_u32 s55, s55, 0
	s_add_i32 s33, s58, s63
	v_lshl_add_u64 v[144:145], s[54:55], 0, v[132:133]
	s_mov_b32 m0, s33
	s_nop 0
	global_load_lds_dwordx4 v[144:145], off
	v_lshl_add_u64 v[144:145], s[54:55], 0, v[128:129]
	s_add_i32 m0, s33, 0x2000
	s_nop 0
	global_load_lds_dwordx4 v[144:145], off
	s_waitcnt vmcnt(6)
	s_barrier
	s_setprio 1
	v_mfma_f32_16x16x32_bf16 v[52:55], v[206:209], v[166:169], v[52:55]
	v_mfma_f32_16x16x32_bf16 v[48:51], v[214:217], v[166:169], v[48:51]
	v_mfma_f32_16x16x32_bf16 v[36:39], v[206:209], v[182:185], v[36:39]
	v_mfma_f32_16x16x32_bf16 v[32:35], v[214:217], v[182:185], v[32:35]
	v_mfma_f32_16x16x32_bf16 v[20:23], v[206:209], v[190:193], v[20:23]
	v_mfma_f32_16x16x32_bf16 v[16:19], v[214:217], v[190:193], v[16:19]
	v_mfma_f32_16x16x32_bf16 v[4:7], v[206:209], v[198:201], v[4:7]
	v_mfma_f32_16x16x32_bf16 v[0:3], v[214:217], v[198:201], v[0:3]
	v_mfma_f32_16x16x32_bf16 v[52:55], v[210:213], v[178:181], v[52:55]
	v_mfma_f32_16x16x32_bf16 v[48:51], v[218:221], v[178:181], v[48:51]
	v_mfma_f32_16x16x32_bf16 v[36:39], v[210:213], v[186:189], v[36:39]
	v_mfma_f32_16x16x32_bf16 v[32:35], v[218:221], v[186:189], v[32:35]
	v_mfma_f32_16x16x32_bf16 v[20:23], v[210:213], v[194:197], v[20:23]
	v_mfma_f32_16x16x32_bf16 v[16:19], v[218:221], v[194:197], v[16:19]
	v_mfma_f32_16x16x32_bf16 v[4:7], v[210:213], v[202:205], v[4:7]
	v_mfma_f32_16x16x32_bf16 v[0:3], v[218:221], v[202:205], v[0:3]
	s_setprio 0
	s_add_i32 s86, s86, 2
	s_add_u32 s84, s84, 0x100
	s_addc_u32 s85, s85, 0
	s_add_u32 s52, s52, 0x10000
	s_addc_u32 s53, s53, 0
	s_cmp_gt_u32 s86, 61
	s_barrier
	s_cbranch_scc0 .LBB0_1460
	s_lshl_b32 s82, s14, 8
	v_lshl_or_b32 v145, s81, 8, v154
	v_add_u32_e32 v144, s82, v152
	v_lshlrev_b32_e32 v145, 2, v145
	s_sub_u32 s83, s82, 0x1000
	s_lshr_b32 s83, s83, 11
	s_mul_i32 s83, s83, 6
	s_add_i32 s83, s83, 11
	s_cmp_gt_i32 s14, 15
	s_cselect_b32 s83, s83, 5
	s_lshl_b32 s83, s83, 12
	s_add_u32 s48, s72, s83
	s_addc_u32 s49, s73, 0
	v_lshl_add_u32 v146, v144, 12, v145
	global_load_dwordx4 v[148:151], v145, s[48:49]
	global_load_dwordx4 v[158:161], v145, s[48:49] offset:64
	global_load_dwordx4 v[162:165], v145, s[48:49] offset:512
	global_load_dwordx4 v[166:169], v145, s[48:49] offset:576
	s_mov_b64 s[84:85], s[24:25]
	s_mov_b64 s[86:87], s[24:25]
	global_load_dwordx4 v[178:181], v146, s[84:85]
	global_load_dwordx4 v[182:185], v146, s[84:85] offset:64
	global_load_dwordx4 v[186:189], v146, s[84:85] offset:512
	global_load_dwordx4 v[190:193], v146, s[84:85] offset:576
	s_add_u32 s84, s84, 0x10000
	s_addc_u32 s85, s85, 0
	global_load_dwordx4 v[194:197], v146, s[84:85]
	global_load_dwordx4 v[198:201], v146, s[84:85] offset:64
	global_load_dwordx4 v[202:205], v146, s[84:85] offset:512
	global_load_dwordx4 v[206:209], v146, s[84:85] offset:576
	s_add_u32 s84, s84, 0x10000
	s_addc_u32 s85, s85, 0
	global_load_dwordx4 v[210:213], v146, s[84:85]
	global_load_dwordx4 v[214:217], v146, s[84:85] offset:64
	global_load_dwordx4 v[218:221], v146, s[84:85] offset:512
	global_load_dwordx4 v[222:225], v146, s[84:85] offset:576
	s_add_u32 s84, s84, 0x10000
	s_addc_u32 s85, s85, 0
	global_load_dwordx4 v[226:229], v146, s[84:85]
	global_load_dwordx4 v[230:233], v146, s[84:85] offset:64
	s_waitcnt vmcnt(13)
	v_pk_fma_f32 v[124:125], v[124:125], v[148:149], v[178:179]
	v_pk_fma_f32 v[126:127], v[126:127], v[150:151], v[180:181]
	global_store_dwordx4 v146, v[124:127], s[86:87] sc1
	global_load_dwordx4 v[178:181], v146, s[84:85] offset:512
	s_waitcnt vmcnt(14)
	v_pk_fma_f32 v[120:121], v[120:121], v[158:159], v[182:183]
	v_pk_fma_f32 v[122:123], v[122:123], v[160:161], v[184:185]
	global_store_dwordx4 v146, v[120:123], s[86:87] offset:64 sc1
	global_load_dwordx4 v[182:185], v146, s[84:85] offset:576
	s_waitcnt vmcnt(15)
	v_pk_fma_f32 v[116:117], v[116:117], v[162:163], v[186:187]
	v_pk_fma_f32 v[118:119], v[118:119], v[164:165], v[188:189]
	global_store_dwordx4 v146, v[116:119], s[86:87] offset:512 sc1
	s_add_u32 s84, s84, 0x50000
	s_addc_u32 s85, s85, 0
	global_load_dwordx4 v[186:189], v146, s[84:85]
	s_waitcnt vmcnt(16)
	v_pk_fma_f32 v[112:113], v[112:113], v[166:167], v[190:191]
	v_pk_fma_f32 v[114:115], v[114:115], v[168:169], v[192:193]
	global_store_dwordx4 v146, v[112:115], s[86:87] offset:576 sc1
	global_load_dwordx4 v[190:193], v146, s[84:85] offset:64
	s_add_u32 s86, s86, 0x10000
	s_addc_u32 s87, s87, 0
	s_waitcnt vmcnt(17)
	v_pk_fma_f32 v[108:109], v[108:109], v[148:149], v[194:195]
	v_pk_fma_f32 v[110:111], v[110:111], v[150:151], v[196:197]
	global_store_dwordx4 v146, v[108:111], s[86:87] sc1
	global_load_dwordx4 v[194:197], v146, s[84:85] offset:512
	s_waitcnt vmcnt(18)
	v_pk_fma_f32 v[104:105], v[104:105], v[158:159], v[198:199]
	v_pk_fma_f32 v[106:107], v[106:107], v[160:161], v[200:201]
	global_store_dwordx4 v146, v[104:107], s[86:87] offset:64 sc1
	global_load_dwordx4 v[198:201], v146, s[84:85] offset:576
	s_waitcnt vmcnt(19)
	v_pk_fma_f32 v[100:101], v[100:101], v[162:163], v[202:203]
	v_pk_fma_f32 v[102:103], v[102:103], v[164:165], v[204:205]
	global_store_dwordx4 v146, v[100:103], s[86:87] offset:512 sc1
	s_add_u32 s84, s84, 0x10000
	s_addc_u32 s85, s85, 0
	global_load_dwordx4 v[202:205], v146, s[84:85]
	s_waitcnt vmcnt(20)
	v_pk_fma_f32 v[96:97], v[96:97], v[166:167], v[206:207]
	v_pk_fma_f32 v[98:99], v[98:99], v[168:169], v[208:209]
	global_store_dwordx4 v146, v[96:99], s[86:87] offset:576 sc1
	global_load_dwordx4 v[206:209], v146, s[84:85] offset:64
	s_add_u32 s86, s86, 0x10000
	s_addc_u32 s87, s87, 0
	s_waitcnt vmcnt(21)
	v_pk_fma_f32 v[92:93], v[92:93], v[148:149], v[210:211]
	v_pk_fma_f32 v[94:95], v[94:95], v[150:151], v[212:213]
	global_store_dwordx4 v146, v[92:95], s[86:87] sc1
	global_load_dwordx4 v[210:213], v146, s[84:85] offset:512
	s_waitcnt vmcnt(22)
	v_pk_fma_f32 v[88:89], v[88:89], v[158:159], v[214:215]
	v_pk_fma_f32 v[90:91], v[90:91], v[160:161], v[216:217]
	global_store_dwordx4 v146, v[88:91], s[86:87] offset:64 sc1
	global_load_dwordx4 v[214:217], v146, s[84:85] offset:576
	s_waitcnt vmcnt(23)
	v_pk_fma_f32 v[84:85], v[84:85], v[162:163], v[218:219]
	v_pk_fma_f32 v[86:87], v[86:87], v[164:165], v[220:221]
	global_store_dwordx4 v146, v[84:87], s[86:87] offset:512 sc1
	s_add_u32 s84, s84, 0x10000
	s_addc_u32 s85, s85, 0
	global_load_dwordx4 v[218:221], v146, s[84:85]
	s_waitcnt vmcnt(24)
	v_pk_fma_f32 v[80:81], v[80:81], v[166:167], v[222:223]
	v_pk_fma_f32 v[82:83], v[82:83], v[168:169], v[224:225]
	global_store_dwordx4 v146, v[80:83], s[86:87] offset:576 sc1
	global_load_dwordx4 v[222:225], v146, s[84:85] offset:64
	s_add_u32 s86, s86, 0x10000
	s_addc_u32 s87, s87, 0
	s_waitcnt vmcnt(25)
	v_pk_fma_f32 v[76:77], v[76:77], v[148:149], v[226:227]
	v_pk_fma_f32 v[78:79], v[78:79], v[150:151], v[228:229]
	global_store_dwordx4 v146, v[76:79], s[86:87] sc1
	global_load_dwordx4 v[226:229], v146, s[84:85] offset:512
	s_waitcnt vmcnt(26)
	v_pk_fma_f32 v[72:73], v[72:73], v[158:159], v[230:231]
	v_pk_fma_f32 v[74:75], v[74:75], v[160:161], v[232:233]
	global_store_dwordx4 v146, v[72:75], s[86:87] offset:64 sc1
	global_load_dwordx4 v[230:233], v146, s[84:85] offset:576
	s_waitcnt vmcnt(26)
	v_pk_fma_f32 v[68:69], v[68:69], v[162:163], v[178:179]
	v_pk_fma_f32 v[70:71], v[70:71], v[164:165], v[180:181]
	global_store_dwordx4 v146, v[68:71], s[86:87] offset:512 sc1
	s_add_u32 s84, s84, 0x10000
	s_addc_u32 s85, s85, 0
	global_load_dwordx4 v[178:181], v146, s[84:85]
	s_waitcnt vmcnt(26)
	v_pk_fma_f32 v[64:65], v[64:65], v[166:167], v[182:183]
	v_pk_fma_f32 v[66:67], v[66:67], v[168:169], v[184:185]
	global_store_dwordx4 v146, v[64:67], s[86:87] offset:576 sc1
	global_load_dwordx4 v[182:185], v146, s[84:85] offset:64
	s_add_u32 s86, s86, 0x50000
	s_addc_u32 s87, s87, 0
	s_waitcnt vmcnt(26)
	v_pk_fma_f32 v[60:61], v[60:61], v[148:149], v[186:187]
	v_pk_fma_f32 v[62:63], v[62:63], v[150:151], v[188:189]
	global_store_dwordx4 v146, v[60:63], s[86:87] sc1
	global_load_dwordx4 v[186:189], v146, s[84:85] offset:512
	s_waitcnt vmcnt(26)
	v_pk_fma_f32 v[56:57], v[56:57], v[158:159], v[190:191]
	v_pk_fma_f32 v[58:59], v[58:59], v[160:161], v[192:193]
	global_store_dwordx4 v146, v[56:59], s[86:87] offset:64 sc1
	global_load_dwordx4 v[190:193], v146, s[84:85] offset:576
	s_waitcnt vmcnt(26)
	v_pk_fma_f32 v[52:53], v[52:53], v[162:163], v[194:195]
	v_pk_fma_f32 v[54:55], v[54:55], v[164:165], v[196:197]
	global_store_dwordx4 v146, v[52:55], s[86:87] offset:512 sc1
	s_waitcnt vmcnt(25)
	v_pk_fma_f32 v[48:49], v[48:49], v[166:167], v[198:199]
	v_pk_fma_f32 v[50:51], v[50:51], v[168:169], v[200:201]
	global_store_dwordx4 v146, v[48:51], s[86:87] offset:576 sc1
	s_add_u32 s86, s86, 0x10000
	s_addc_u32 s87, s87, 0
	s_waitcnt vmcnt(24)
	v_pk_fma_f32 v[44:45], v[44:45], v[148:149], v[202:203]
	v_pk_fma_f32 v[46:47], v[46:47], v[150:151], v[204:205]
	global_store_dwordx4 v146, v[44:47], s[86:87] sc1
	s_waitcnt vmcnt(23)
	v_pk_fma_f32 v[40:41], v[40:41], v[158:159], v[206:207]
	v_pk_fma_f32 v[42:43], v[42:43], v[160:161], v[208:209]
	global_store_dwordx4 v146, v[40:43], s[86:87] offset:64 sc1
	s_waitcnt vmcnt(22)
	v_pk_fma_f32 v[36:37], v[36:37], v[162:163], v[210:211]
	v_pk_fma_f32 v[38:39], v[38:39], v[164:165], v[212:213]
	global_store_dwordx4 v146, v[36:39], s[86:87] offset:512 sc1
	s_waitcnt vmcnt(21)
	v_pk_fma_f32 v[32:33], v[32:33], v[166:167], v[214:215]
	v_pk_fma_f32 v[34:35], v[34:35], v[168:169], v[216:217]
	global_store_dwordx4 v146, v[32:35], s[86:87] offset:576 sc1
	s_add_u32 s86, s86, 0x10000
	s_addc_u32 s87, s87, 0
	s_waitcnt vmcnt(20)
	v_pk_fma_f32 v[28:29], v[28:29], v[148:149], v[218:219]
	v_pk_fma_f32 v[30:31], v[30:31], v[150:151], v[220:221]
	global_store_dwordx4 v146, v[28:31], s[86:87] sc1
	s_waitcnt vmcnt(19)
	v_pk_fma_f32 v[24:25], v[24:25], v[158:159], v[222:223]
	v_pk_fma_f32 v[26:27], v[26:27], v[160:161], v[224:225]
	global_store_dwordx4 v146, v[24:27], s[86:87] offset:64 sc1
	s_waitcnt vmcnt(18)
	v_pk_fma_f32 v[20:21], v[20:21], v[162:163], v[226:227]
	v_pk_fma_f32 v[22:23], v[22:23], v[164:165], v[228:229]
	global_store_dwordx4 v146, v[20:23], s[86:87] offset:512 sc1
	s_waitcnt vmcnt(17)
	v_pk_fma_f32 v[16:17], v[16:17], v[166:167], v[230:231]
	v_pk_fma_f32 v[18:19], v[18:19], v[168:169], v[232:233]
	global_store_dwordx4 v146, v[16:19], s[86:87] offset:576 sc1
	s_add_u32 s86, s86, 0x10000
	s_addc_u32 s87, s87, 0
	s_waitcnt vmcnt(16)
	v_pk_fma_f32 v[12:13], v[12:13], v[148:149], v[178:179]
	v_pk_fma_f32 v[14:15], v[14:15], v[150:151], v[180:181]
	global_store_dwordx4 v146, v[12:15], s[86:87] sc1
	s_waitcnt vmcnt(15)
	v_pk_fma_f32 v[8:9], v[8:9], v[158:159], v[182:183]
	v_pk_fma_f32 v[10:11], v[10:11], v[160:161], v[184:185]
	global_store_dwordx4 v146, v[8:11], s[86:87] offset:64 sc1
	s_waitcnt vmcnt(14)
	v_pk_fma_f32 v[4:5], v[4:5], v[162:163], v[186:187]
	v_pk_fma_f32 v[6:7], v[6:7], v[164:165], v[188:189]
	global_store_dwordx4 v146, v[4:7], s[86:87] offset:512 sc1
	s_waitcnt vmcnt(13)
	v_pk_fma_f32 v[0:1], v[0:1], v[166:167], v[190:191]
	v_pk_fma_f32 v[2:3], v[2:3], v[168:169], v[192:193]
	global_store_dwordx4 v146, v[0:3], s[86:87] offset:576 sc1
	s_mov_b32 s81, s34
	s_mov_b64 s[52:53], s[50:51]
	s_mov_b64 s[54:55], s[40:41]
	s_mov_b32 s14, s36
	s_and_b64 vcc, exec, s[12:13]
	s_cbranch_vccz .LBB0_1457
	s_waitcnt vmcnt(0)
	s_cmpk_gt_u32 s60, 0xff
	s_cbranch_scc1 .LBB0_1464
	s_barrier

.LBB0_1828:
	s_add_u32 s33, s56, s62
	s_addc_u32 s63, s57, 0
	s_add_u32 s66, s33, 0x100
	s_addc_u32 s67, s63, 0
	s_and_b64 s[64:65], s[60:61], exec
	s_cselect_b32 s67, s51, s67
	s_cselect_b32 s66, s50, s66
	s_add_u32 s62, s54, s62
	s_addc_u32 s64, s55, 0
	s_add_u32 s62, s62, 0x100
	s_addc_u32 s64, s64, 0
	s_and_b64 s[60:61], s[60:61], exec
	s_cselect_b32 s69, s37, s64
	s_cselect_b32 s68, s41, s62
	s_add_u32 s70, s33, 0x40080
	s_addc_u32 s71, s63, 0
	s_add_i32 s49, s84, s73
	s_add_i32 m0, s48, 0xc000
	s_add_i32 s74, s48, 0xe000
	s_add_i32 s33, s49, 0x2000
	s_add_u32 s64, s68, 0x10000
	s_addc_u32 s65, s69, 0
	s_add_i32 s97, s85, s73
	ds_read_b128 v[140:143], v149
	ds_read_b128 v[152:155], v149 offset:1024
	ds_read_b128 v[156:159], v149 offset:2048
	ds_read_b128 v[160:163], v149 offset:3072
	s_add_i32 s96, s97, 0x2000
	s_add_i32 s95, 0, 0x18000
	s_add_u32 s62, s66, 0x40000
	s_addc_u32 s63, s67, 0
	s_add_i32 s94, s95, s73
	s_add_i32 s93, 0, 0x1c000
	s_add_i32 s92, s94, 0x2000
	s_add_u32 s60, s68, 0x10080
	s_addc_u32 s61, s69, 0
	s_add_i32 vcc_hi, s93, s73
	s_add_i32 vcc_lo, vcc_hi, 0x2000
	v_lshl_add_u64 v[144:145], s[70:71], 0, v[134:135]
	ds_read_b128 v[164:167], v150
	ds_read_b128 v[178:181], v150 offset:1024
	ds_read_b128 v[182:185], v150 offset:2048
	ds_read_b128 v[186:189], v150 offset:3072
	ds_read_b128 v[190:193], v150 offset:4096
	ds_read_b128 v[194:197], v150 offset:5120
	ds_read_b128 v[198:201], v150 offset:6144
	ds_read_b128 v[202:205], v150 offset:7168
	global_load_lds_dwordx4 v[144:145], off
	v_lshl_add_u64 v[144:145], s[70:71], 0, v[130:131]
	s_mov_b32 m0, s74
	s_nop 0
	global_load_lds_dwordx4 v[144:145], off
	s_waitcnt lgkmcnt(8)
	s_barrier
	s_waitcnt lgkmcnt(0)
	s_setprio 1
	s_waitcnt lgkmcnt(0)
	v_mfma_f32_16x16x32_bf16 v[124:127], v[140:143], v[164:167], v[124:127]
	v_mfma_f32_16x16x32_bf16 v[120:123], v[156:159], v[164:167], v[120:123]
	v_mfma_f32_16x16x32_bf16 v[116:119], v[140:143], v[182:185], v[116:119]
	v_mfma_f32_16x16x32_bf16 v[112:115], v[156:159], v[182:185], v[112:115]
	v_mfma_f32_16x16x32_bf16 v[108:111], v[140:143], v[190:193], v[108:111]
	v_mfma_f32_16x16x32_bf16 v[104:107], v[156:159], v[190:193], v[104:107]
	v_mfma_f32_16x16x32_bf16 v[100:103], v[140:143], v[198:201], v[100:103]
	v_mfma_f32_16x16x32_bf16 v[96:99], v[156:159], v[198:201], v[96:99]
	v_mfma_f32_16x16x32_bf16 v[124:127], v[152:155], v[178:181], v[124:127]
	v_mfma_f32_16x16x32_bf16 v[120:123], v[160:163], v[178:181], v[120:123]
	v_mfma_f32_16x16x32_bf16 v[116:119], v[152:155], v[186:189], v[116:119]
	v_mfma_f32_16x16x32_bf16 v[112:115], v[160:163], v[186:189], v[112:115]
	v_mfma_f32_16x16x32_bf16 v[108:111], v[152:155], v[194:197], v[108:111]
	v_mfma_f32_16x16x32_bf16 v[104:107], v[160:163], v[194:197], v[104:107]
	v_mfma_f32_16x16x32_bf16 v[100:103], v[152:155], v[202:205], v[100:103]
	v_mfma_f32_16x16x32_bf16 v[96:99], v[160:163], v[202:205], v[96:99]
	s_setprio 0
	s_barrier
	s_mov_b32 m0, s49
	v_lshl_add_u64 v[144:145], s[68:69], 0, v[132:133]
	ds_read_b128 v[206:209], v151
	ds_read_b128 v[210:213], v151 offset:1024
	ds_read_b128 v[214:217], v151 offset:2048
	ds_read_b128 v[218:221], v151 offset:3072
	global_load_lds_dwordx4 v[144:145], off
	v_lshl_add_u64 v[168:169], s[68:69], 0, v[128:129]
	s_mov_b32 m0, s33
	s_nop 0
	global_load_lds_dwordx4 v[168:169], off
	s_barrier
	s_waitcnt lgkmcnt(0)
	s_setprio 1
	s_waitcnt lgkmcnt(0)
	v_mfma_f32_16x16x32_bf16 v[92:95], v[206:209], v[164:167], v[92:95]
	v_mfma_f32_16x16x32_bf16 v[88:91], v[214:217], v[164:167], v[88:91]
	v_mfma_f32_16x16x32_bf16 v[84:87], v[206:209], v[182:185], v[84:87]
	v_mfma_f32_16x16x32_bf16 v[80:83], v[214:217], v[182:185], v[80:83]
	v_mfma_f32_16x16x32_bf16 v[76:79], v[206:209], v[190:193], v[76:79]
	v_mfma_f32_16x16x32_bf16 v[72:75], v[214:217], v[190:193], v[72:75]
	v_mfma_f32_16x16x32_bf16 v[68:71], v[206:209], v[198:201], v[68:71]
	v_mfma_f32_16x16x32_bf16 v[64:67], v[214:217], v[198:201], v[64:67]
	v_mfma_f32_16x16x32_bf16 v[92:95], v[210:213], v[178:181], v[92:95]
	v_mfma_f32_16x16x32_bf16 v[88:91], v[218:221], v[178:181], v[88:91]
	v_mfma_f32_16x16x32_bf16 v[84:87], v[210:213], v[186:189], v[84:87]
	v_mfma_f32_16x16x32_bf16 v[80:83], v[218:221], v[186:189], v[80:83]
	v_mfma_f32_16x16x32_bf16 v[76:79], v[210:213], v[194:197], v[76:79]
	v_mfma_f32_16x16x32_bf16 v[72:75], v[218:221], v[194:197], v[72:75]
	v_mfma_f32_16x16x32_bf16 v[68:71], v[210:213], v[202:205], v[68:71]
	v_mfma_f32_16x16x32_bf16 v[64:67], v[218:221], v[202:205], v[64:67]
	s_setprio 0
	s_mov_b32 m0, s48
	v_lshl_add_u64 v[222:223], s[66:67], 0, v[134:135]
	s_barrier
	ds_read_b128 v[164:167], v150 offset:16384
	ds_read_b128 v[178:181], v150 offset:17408
	ds_read_b128 v[182:185], v150 offset:18432
	ds_read_b128 v[186:189], v150 offset:19456
	ds_read_b128 v[190:193], v150 offset:20480
	ds_read_b128 v[194:197], v150 offset:21504
	ds_read_b128 v[198:201], v150 offset:22528
	ds_read_b128 v[202:205], v150 offset:23552
	global_load_lds_dwordx4 v[222:223], off
	v_lshl_add_u64 v[224:225], s[66:67], 0, v[130:131]
	s_mov_b32 m0, s75
	s_nop 0
	global_load_lds_dwordx4 v[224:225], off
	s_barrier
	s_waitcnt lgkmcnt(0)
	s_setprio 1
	s_waitcnt lgkmcnt(0)
	v_mfma_f32_16x16x32_bf16 v[60:63], v[140:143], v[164:167], v[60:63]
	v_mfma_f32_16x16x32_bf16 v[56:59], v[156:159], v[164:167], v[56:59]
	v_mfma_f32_16x16x32_bf16 v[52:55], v[140:143], v[182:185], v[52:55]
	v_mfma_f32_16x16x32_bf16 v[48:51], v[156:159], v[182:185], v[48:51]
	v_mfma_f32_16x16x32_bf16 v[44:47], v[140:143], v[190:193], v[44:47]
	v_mfma_f32_16x16x32_bf16 v[40:43], v[156:159], v[190:193], v[40:43]
	v_mfma_f32_16x16x32_bf16 v[36:39], v[140:143], v[198:201], v[36:39]
	v_mfma_f32_16x16x32_bf16 v[32:35], v[156:159], v[198:201], v[32:35]
	v_mfma_f32_16x16x32_bf16 v[60:63], v[152:155], v[178:181], v[60:63]
	v_mfma_f32_16x16x32_bf16 v[56:59], v[160:163], v[178:181], v[56:59]
	v_mfma_f32_16x16x32_bf16 v[52:55], v[152:155], v[186:189], v[52:55]
	v_mfma_f32_16x16x32_bf16 v[48:51], v[160:163], v[186:189], v[48:51]
	v_mfma_f32_16x16x32_bf16 v[44:47], v[152:155], v[194:197], v[44:47]
	v_mfma_f32_16x16x32_bf16 v[40:43], v[160:163], v[194:197], v[40:43]
	v_mfma_f32_16x16x32_bf16 v[36:39], v[152:155], v[202:205], v[36:39]
	v_mfma_f32_16x16x32_bf16 v[32:35], v[160:163], v[202:205], v[32:35]
	s_setprio 0
	s_barrier
	s_mov_b32 m0, s97
	v_lshl_add_u64 v[140:141], s[64:65], 0, v[132:133]
	global_load_lds_dwordx4 v[140:141], off
	v_lshl_add_u64 v[140:141], s[64:65], 0, v[128:129]
	s_mov_b32 m0, s96
	s_nop 0
	global_load_lds_dwordx4 v[140:141], off
	s_waitcnt vmcnt(6)
	s_barrier
	s_setprio 1
	v_mfma_f32_16x16x32_bf16 v[28:31], v[206:209], v[164:167], v[28:31]
	v_mfma_f32_16x16x32_bf16 v[24:27], v[214:217], v[164:167], v[24:27]
	v_mfma_f32_16x16x32_bf16 v[20:23], v[206:209], v[182:185], v[20:23]
	v_mfma_f32_16x16x32_bf16 v[16:19], v[214:217], v[182:185], v[16:19]
	v_mfma_f32_16x16x32_bf16 v[12:15], v[206:209], v[190:193], v[12:15]
	v_mfma_f32_16x16x32_bf16 v[8:11], v[214:217], v[190:193], v[8:11]
	v_mfma_f32_16x16x32_bf16 v[4:7], v[206:209], v[198:201], v[4:7]
	v_mfma_f32_16x16x32_bf16 v[0:3], v[214:217], v[198:201], v[0:3]
	v_mfma_f32_16x16x32_bf16 v[28:31], v[210:213], v[178:181], v[28:31]
	v_mfma_f32_16x16x32_bf16 v[24:27], v[218:221], v[178:181], v[24:27]
	v_mfma_f32_16x16x32_bf16 v[20:23], v[210:213], v[186:189], v[20:23]
	v_mfma_f32_16x16x32_bf16 v[16:19], v[218:221], v[186:189], v[16:19]
	v_mfma_f32_16x16x32_bf16 v[12:15], v[210:213], v[194:197], v[12:15]
	v_mfma_f32_16x16x32_bf16 v[8:11], v[218:221], v[194:197], v[8:11]
	v_mfma_f32_16x16x32_bf16 v[4:7], v[210:213], v[202:205], v[4:7]
	v_mfma_f32_16x16x32_bf16 v[0:3], v[218:221], v[202:205], v[0:3]
	s_setprio 0
	v_add_u32_e32 v160, s95, v147
	s_barrier
	ds_read_b128 v[140:143], v160
	ds_read_b128 v[152:155], v160 offset:1024
	ds_read_b128 v[156:159], v160 offset:2048
	ds_read_b128 v[160:163], v160 offset:3072
	s_mov_b32 m0, s76
	v_lshl_add_u64 v[206:207], s[62:63], 0, v[134:135]
	ds_read_b128 v[164:167], v150 offset:32768
	ds_read_b128 v[178:181], v150 offset:33792
	ds_read_b128 v[182:185], v150 offset:34816
	ds_read_b128 v[186:189], v150 offset:35840
	ds_read_b128 v[190:193], v150 offset:36864
	ds_read_b128 v[194:197], v150 offset:37888
	ds_read_b128 v[198:201], v150 offset:38912
	ds_read_b128 v[202:205], v150 offset:39936
	global_load_lds_dwordx4 v[206:207], off
	v_lshl_add_u64 v[206:207], s[62:63], 0, v[130:131]
	s_mov_b32 m0, s77
	s_nop 0
	global_load_lds_dwordx4 v[206:207], off
	s_waitcnt lgkmcnt(8)
	s_barrier
	s_waitcnt lgkmcnt(0)
	s_setprio 1
	s_waitcnt lgkmcnt(0)
	v_mfma_f32_16x16x32_bf16 v[124:127], v[140:143], v[164:167], v[124:127]
	v_mfma_f32_16x16x32_bf16 v[120:123], v[156:159], v[164:167], v[120:123]
	v_mfma_f32_16x16x32_bf16 v[116:119], v[140:143], v[182:185], v[116:119]
	v_mfma_f32_16x16x32_bf16 v[112:115], v[156:159], v[182:185], v[112:115]
	v_mfma_f32_16x16x32_bf16 v[108:111], v[140:143], v[190:193], v[108:111]
	v_mfma_f32_16x16x32_bf16 v[104:107], v[156:159], v[190:193], v[104:107]
	v_mfma_f32_16x16x32_bf16 v[100:103], v[140:143], v[198:201], v[100:103]
	v_mfma_f32_16x16x32_bf16 v[96:99], v[156:159], v[198:201], v[96:99]
	v_mfma_f32_16x16x32_bf16 v[124:127], v[152:155], v[178:181], v[124:127]
	v_mfma_f32_16x16x32_bf16 v[120:123], v[160:163], v[178:181], v[120:123]
	v_mfma_f32_16x16x32_bf16 v[116:119], v[152:155], v[186:189], v[116:119]
	v_mfma_f32_16x16x32_bf16 v[112:115], v[160:163], v[186:189], v[112:115]
	v_mfma_f32_16x16x32_bf16 v[108:111], v[152:155], v[194:197], v[108:111]
	v_mfma_f32_16x16x32_bf16 v[104:107], v[160:163], v[194:197], v[104:107]
	v_mfma_f32_16x16x32_bf16 v[100:103], v[152:155], v[202:205], v[100:103]
	v_mfma_f32_16x16x32_bf16 v[96:99], v[160:163], v[202:205], v[96:99]
	s_setprio 0
	s_barrier
	s_mov_b32 m0, s94
	v_add_u32_e32 v177, s93, v147
	v_lshl_add_u64 v[144:145], v[144:145], 0, s[24:25]
	ds_read_b128 v[206:209], v177
	ds_read_b128 v[210:213], v177 offset:1024
	ds_read_b128 v[214:217], v177 offset:2048
	ds_read_b128 v[218:221], v177 offset:3072
	global_load_lds_dwordx4 v[144:145], off
	v_lshl_add_u64 v[144:145], v[168:169], 0, s[24:25]
	s_mov_b32 m0, s92
	s_nop 0
	global_load_lds_dwordx4 v[144:145], off
	s_barrier
	s_waitcnt lgkmcnt(0)
	s_setprio 1
	s_waitcnt lgkmcnt(0)
	v_mfma_f32_16x16x32_bf16 v[92:95], v[206:209], v[164:167], v[92:95]
	v_mfma_f32_16x16x32_bf16 v[88:91], v[214:217], v[164:167], v[88:91]
	v_mfma_f32_16x16x32_bf16 v[84:87], v[206:209], v[182:185], v[84:87]
	v_mfma_f32_16x16x32_bf16 v[80:83], v[214:217], v[182:185], v[80:83]
	v_mfma_f32_16x16x32_bf16 v[76:79], v[206:209], v[190:193], v[76:79]
	v_mfma_f32_16x16x32_bf16 v[72:75], v[214:217], v[190:193], v[72:75]
	v_mfma_f32_16x16x32_bf16 v[68:71], v[206:209], v[198:201], v[68:71]
	v_mfma_f32_16x16x32_bf16 v[64:67], v[214:217], v[198:201], v[64:67]
	v_mfma_f32_16x16x32_bf16 v[92:95], v[210:213], v[178:181], v[92:95]
	v_mfma_f32_16x16x32_bf16 v[88:91], v[218:221], v[178:181], v[88:91]
	v_mfma_f32_16x16x32_bf16 v[84:87], v[210:213], v[186:189], v[84:87]
	v_mfma_f32_16x16x32_bf16 v[80:83], v[218:221], v[186:189], v[80:83]
	v_mfma_f32_16x16x32_bf16 v[76:79], v[210:213], v[194:197], v[76:79]
	v_mfma_f32_16x16x32_bf16 v[72:75], v[218:221], v[194:197], v[72:75]
	v_mfma_f32_16x16x32_bf16 v[68:71], v[210:213], v[202:205], v[68:71]
	v_mfma_f32_16x16x32_bf16 v[64:67], v[218:221], v[202:205], v[64:67]
	s_setprio 0
	s_mov_b32 m0, s78
	v_lshl_add_u64 v[144:145], v[222:223], 0, s[24:25]
	s_barrier
	ds_read_b128 v[164:167], v150 offset:49152
	ds_read_b128 v[178:181], v150 offset:50176
	ds_read_b128 v[182:185], v150 offset:51200
	ds_read_b128 v[186:189], v150 offset:52224
	ds_read_b128 v[190:193], v150 offset:53248
	ds_read_b128 v[194:197], v150 offset:54272
	ds_read_b128 v[198:201], v150 offset:55296
	ds_read_b128 v[202:205], v150 offset:56320
	global_load_lds_dwordx4 v[144:145], off
	v_lshl_add_u64 v[144:145], v[224:225], 0, s[24:25]
	s_mov_b32 m0, s79
	s_nop 0
	global_load_lds_dwordx4 v[144:145], off
	s_barrier
	s_waitcnt lgkmcnt(0)
	s_setprio 1
	s_waitcnt lgkmcnt(0)
	v_mfma_f32_16x16x32_bf16 v[60:63], v[140:143], v[164:167], v[60:63]
	v_mfma_f32_16x16x32_bf16 v[56:59], v[156:159], v[164:167], v[56:59]
	v_mfma_f32_16x16x32_bf16 v[52:55], v[140:143], v[182:185], v[52:55]
	v_mfma_f32_16x16x32_bf16 v[48:51], v[156:159], v[182:185], v[48:51]
	v_mfma_f32_16x16x32_bf16 v[44:47], v[140:143], v[190:193], v[44:47]
	v_mfma_f32_16x16x32_bf16 v[40:43], v[156:159], v[190:193], v[40:43]
	v_mfma_f32_16x16x32_bf16 v[36:39], v[140:143], v[198:201], v[36:39]
	v_mfma_f32_16x16x32_bf16 v[32:35], v[156:159], v[198:201], v[32:35]
	v_mfma_f32_16x16x32_bf16 v[60:63], v[152:155], v[178:181], v[60:63]
	v_mfma_f32_16x16x32_bf16 v[56:59], v[160:163], v[178:181], v[56:59]
	v_mfma_f32_16x16x32_bf16 v[52:55], v[152:155], v[186:189], v[52:55]
	v_mfma_f32_16x16x32_bf16 v[48:51], v[160:163], v[186:189], v[48:51]
	v_mfma_f32_16x16x32_bf16 v[44:47], v[152:155], v[194:197], v[44:47]
	v_mfma_f32_16x16x32_bf16 v[40:43], v[160:163], v[194:197], v[40:43]
	v_mfma_f32_16x16x32_bf16 v[36:39], v[152:155], v[202:205], v[36:39]
	v_mfma_f32_16x16x32_bf16 v[32:35], v[160:163], v[202:205], v[32:35]
	s_setprio 0
	s_barrier
	s_mov_b32 m0, vcc_hi
	v_lshl_add_u64 v[140:141], s[60:61], 0, v[132:133]
	global_load_lds_dwordx4 v[140:141], off
	v_lshl_add_u64 v[140:141], s[60:61], 0, v[128:129]
	s_mov_b32 m0, vcc_lo
	s_nop 0
	global_load_lds_dwordx4 v[140:141], off
	s_waitcnt vmcnt(6)
	s_barrier
	s_setprio 1
	v_mfma_f32_16x16x32_bf16 v[28:31], v[206:209], v[164:167], v[28:31]
	v_mfma_f32_16x16x32_bf16 v[24:27], v[214:217], v[164:167], v[24:27]
	v_mfma_f32_16x16x32_bf16 v[20:23], v[206:209], v[182:185], v[20:23]
	v_mfma_f32_16x16x32_bf16 v[16:19], v[214:217], v[182:185], v[16:19]
	v_mfma_f32_16x16x32_bf16 v[12:15], v[206:209], v[190:193], v[12:15]
	v_mfma_f32_16x16x32_bf16 v[8:11], v[214:217], v[190:193], v[8:11]
	v_mfma_f32_16x16x32_bf16 v[4:7], v[206:209], v[198:201], v[4:7]
	v_mfma_f32_16x16x32_bf16 v[0:3], v[214:217], v[198:201], v[0:3]
	v_mfma_f32_16x16x32_bf16 v[28:31], v[210:213], v[178:181], v[28:31]
	v_mfma_f32_16x16x32_bf16 v[24:27], v[218:221], v[178:181], v[24:27]
	v_mfma_f32_16x16x32_bf16 v[20:23], v[210:213], v[186:189], v[20:23]
	v_mfma_f32_16x16x32_bf16 v[16:19], v[218:221], v[186:189], v[16:19]
	v_mfma_f32_16x16x32_bf16 v[12:15], v[210:213], v[194:197], v[12:15]
	v_mfma_f32_16x16x32_bf16 v[8:11], v[218:221], v[194:197], v[8:11]
	v_mfma_f32_16x16x32_bf16 v[4:7], v[210:213], v[202:205], v[4:7]
	v_mfma_f32_16x16x32_bf16 v[0:3], v[218:221], v[202:205], v[0:3]
	s_setprio 0
	s_movk_i32 s62, 0x100
	s_andn2_b64 vcc, exec, s[58:59]
	s_mov_b64 s[60:61], -1
	s_mov_b64 s[58:59], 0
	s_barrier
	s_cbranch_vccz .LBB0_1828
	s_load_dwordx2 s[60:61], s[20:21], 0xc0
	s_lshl_b32 s68, s22, 8
	v_lshl_or_b32 v141, s91, 8, v148
	v_add_u32_e32 v140, s68, v146
	v_lshlrev_b32_e32 v141, 2, v141
	s_sub_u32 s69, s68, 0x1000
	s_lshr_b32 s69, s69, 11
	s_mul_i32 s69, s69, 6
	s_add_i32 s69, s69, 38
	s_cmp_gt_i32 s22, 15
	s_cselect_b32 s69, s69, 32
	s_lshl_b32 s69, s69, 12
	s_add_u32 s62, s82, s69
	s_addc_u32 s63, s83, 0
	v_lshl_add_u32 v142, v140, 12, v141
	global_load_dwordx4 v[152:155], v141, s[62:63]
	global_load_dwordx4 v[156:159], v141, s[62:63] offset:64
	global_load_dwordx4 v[160:163], v141, s[62:63] offset:512
	global_load_dwordx4 v[164:167], v141, s[62:63] offset:576
	s_waitcnt lgkmcnt(0)
	global_load_dwordx4 v[178:181], v141, s[60:61]
	global_load_dwordx4 v[182:185], v141, s[60:61] offset:64
	global_load_dwordx4 v[186:189], v141, s[60:61] offset:512
	global_load_dwordx4 v[190:193], v141, s[60:61] offset:576
	s_mov_b64 s[64:65], s[18:19]
	s_mov_b64 s[66:67], s[18:19]
	global_load_dwordx4 v[194:197], v142, s[64:65]
	global_load_dwordx4 v[198:201], v142, s[64:65] offset:64
	global_load_dwordx4 v[202:205], v142, s[64:65] offset:512
	global_load_dwordx4 v[206:209], v142, s[64:65] offset:576
	s_add_u32 s64, s64, 0x10000
	s_addc_u32 s65, s65, 0
	global_load_dwordx4 v[210:213], v142, s[64:65]
	global_load_dwordx4 v[214:217], v142, s[64:65] offset:64
	global_load_dwordx4 v[218:221], v142, s[64:65] offset:512
	global_load_dwordx4 v[222:225], v142, s[64:65] offset:576
	s_add_u32 s64, s64, 0x10000
	s_addc_u32 s65, s65, 0
	global_load_dwordx4 v[226:229], v142, s[64:65]
	global_load_dwordx4 v[230:233], v142, s[64:65] offset:64
	s_waitcnt vmcnt(9)
	v_pk_mul_f32 v[124:125], v[124:125], v[178:179]
	v_pk_mul_f32 v[126:127], v[126:127], v[180:181]
	v_pk_fma_f32 v[124:125], v[152:153], v[124:125], v[194:195]
	v_pk_fma_f32 v[126:127], v[154:155], v[126:127], v[196:197]
	global_store_dwordx4 v142, v[124:127], s[66:67] sc1
	global_load_dwordx4 v[194:197], v142, s[64:65] offset:512
	s_waitcnt vmcnt(10)
	v_pk_mul_f32 v[120:121], v[120:121], v[182:183]
	v_pk_mul_f32 v[122:123], v[122:123], v[184:185]
	v_pk_fma_f32 v[120:121], v[156:157], v[120:121], v[198:199]
	v_pk_fma_f32 v[122:123], v[158:159], v[122:123], v[200:201]
	global_store_dwordx4 v142, v[120:123], s[66:67] offset:64 sc1
	global_load_dwordx4 v[198:201], v142, s[64:65] offset:576
	s_waitcnt vmcnt(11)
	v_pk_mul_f32 v[92:93], v[92:93], v[186:187]
	v_pk_mul_f32 v[94:95], v[94:95], v[188:189]
	v_pk_fma_f32 v[92:93], v[160:161], v[92:93], v[202:203]
	v_pk_fma_f32 v[94:95], v[162:163], v[94:95], v[204:205]
	global_store_dwordx4 v142, v[92:95], s[66:67] offset:512 sc1
	s_add_u32 s64, s64, 0x10000
	s_addc_u32 s65, s65, 0
	global_load_dwordx4 v[202:205], v142, s[64:65]
	s_waitcnt vmcnt(12)
	v_pk_mul_f32 v[88:89], v[88:89], v[190:191]
	v_pk_mul_f32 v[90:91], v[90:91], v[192:193]
	v_pk_fma_f32 v[88:89], v[164:165], v[88:89], v[206:207]
	v_pk_fma_f32 v[90:91], v[166:167], v[90:91], v[208:209]
	global_store_dwordx4 v142, v[88:91], s[66:67] offset:576 sc1
	global_load_dwordx4 v[206:209], v142, s[64:65] offset:64
	s_add_u32 s66, s66, 0x10000
	s_addc_u32 s67, s67, 0
	s_waitcnt vmcnt(13)
	v_pk_mul_f32 v[116:117], v[116:117], v[178:179]
	v_pk_mul_f32 v[118:119], v[118:119], v[180:181]
	v_pk_fma_f32 v[116:117], v[152:153], v[116:117], v[210:211]
	v_pk_fma_f32 v[118:119], v[154:155], v[118:119], v[212:213]
	global_store_dwordx4 v142, v[116:119], s[66:67] sc1
	global_load_dwordx4 v[210:213], v142, s[64:65] offset:512
	s_waitcnt vmcnt(14)
	v_pk_mul_f32 v[112:113], v[112:113], v[182:183]
	v_pk_mul_f32 v[114:115], v[114:115], v[184:185]
	v_pk_fma_f32 v[112:113], v[156:157], v[112:113], v[214:215]
	v_pk_fma_f32 v[114:115], v[158:159], v[114:115], v[216:217]
	global_store_dwordx4 v142, v[112:115], s[66:67] offset:64 sc1
	global_load_dwordx4 v[214:217], v142, s[64:65] offset:576
	s_waitcnt vmcnt(15)
	v_pk_mul_f32 v[84:85], v[84:85], v[186:187]
	v_pk_mul_f32 v[86:87], v[86:87], v[188:189]
	v_pk_fma_f32 v[84:85], v[160:161], v[84:85], v[218:219]
	v_pk_fma_f32 v[86:87], v[162:163], v[86:87], v[220:221]
	global_store_dwordx4 v142, v[84:87], s[66:67] offset:512 sc1
	s_add_u32 s64, s64, 0x50000
	s_addc_u32 s65, s65, 0
	global_load_dwordx4 v[218:221], v142, s[64:65]
	s_waitcnt vmcnt(16)
	v_pk_mul_f32 v[80:81], v[80:81], v[190:191]
	v_pk_mul_f32 v[82:83], v[82:83], v[192:193]
	v_pk_fma_f32 v[80:81], v[164:165], v[80:81], v[222:223]
	v_pk_fma_f32 v[82:83], v[166:167], v[82:83], v[224:225]
	global_store_dwordx4 v142, v[80:83], s[66:67] offset:576 sc1
	global_load_dwordx4 v[222:225], v142, s[64:65] offset:64
	s_add_u32 s66, s66, 0x10000
	s_addc_u32 s67, s67, 0
	s_waitcnt vmcnt(17)
	v_pk_mul_f32 v[108:109], v[108:109], v[178:179]
	v_pk_mul_f32 v[110:111], v[110:111], v[180:181]
	v_pk_fma_f32 v[108:109], v[152:153], v[108:109], v[226:227]
	v_pk_fma_f32 v[110:111], v[154:155], v[110:111], v[228:229]
	global_store_dwordx4 v142, v[108:111], s[66:67] sc1
	global_load_dwordx4 v[226:229], v142, s[64:65] offset:512
	s_waitcnt vmcnt(18)
	v_pk_mul_f32 v[104:105], v[104:105], v[182:183]
	v_pk_mul_f32 v[106:107], v[106:107], v[184:185]
	v_pk_fma_f32 v[104:105], v[156:157], v[104:105], v[230:231]
	v_pk_fma_f32 v[106:107], v[158:159], v[106:107], v[232:233]
	global_store_dwordx4 v142, v[104:107], s[66:67] offset:64 sc1
	global_load_dwordx4 v[230:233], v142, s[64:65] offset:576
	s_waitcnt vmcnt(18)
	v_pk_mul_f32 v[76:77], v[76:77], v[186:187]
	v_pk_mul_f32 v[78:79], v[78:79], v[188:189]
	v_pk_fma_f32 v[76:77], v[160:161], v[76:77], v[194:195]
	v_pk_fma_f32 v[78:79], v[162:163], v[78:79], v[196:197]
	global_store_dwordx4 v142, v[76:79], s[66:67] offset:512 sc1
	s_add_u32 s64, s64, 0x10000
	s_addc_u32 s65, s65, 0
	global_load_dwordx4 v[194:197], v142, s[64:65]
	s_waitcnt vmcnt(18)
	v_pk_mul_f32 v[72:73], v[72:73], v[190:191]
	v_pk_mul_f32 v[74:75], v[74:75], v[192:193]
	v_pk_fma_f32 v[72:73], v[164:165], v[72:73], v[198:199]
	v_pk_fma_f32 v[74:75], v[166:167], v[74:75], v[200:201]
	global_store_dwordx4 v142, v[72:75], s[66:67] offset:576 sc1
	global_load_dwordx4 v[198:201], v142, s[64:65] offset:64
	s_add_u32 s66, s66, 0x10000
	s_addc_u32 s67, s67, 0
	s_waitcnt vmcnt(18)
	v_pk_mul_f32 v[100:101], v[100:101], v[178:179]
	v_pk_mul_f32 v[102:103], v[102:103], v[180:181]
	v_pk_fma_f32 v[100:101], v[152:153], v[100:101], v[202:203]
	v_pk_fma_f32 v[102:103], v[154:155], v[102:103], v[204:205]
	global_store_dwordx4 v142, v[100:103], s[66:67] sc1
	global_load_dwordx4 v[202:205], v142, s[64:65] offset:512
	s_waitcnt vmcnt(18)
	v_pk_mul_f32 v[96:97], v[96:97], v[182:183]
	v_pk_mul_f32 v[98:99], v[98:99], v[184:185]
	v_pk_fma_f32 v[96:97], v[156:157], v[96:97], v[206:207]
	v_pk_fma_f32 v[98:99], v[158:159], v[98:99], v[208:209]
	global_store_dwordx4 v142, v[96:99], s[66:67] offset:64 sc1
	global_load_dwordx4 v[206:209], v142, s[64:65] offset:576
	s_waitcnt vmcnt(18)
	v_pk_mul_f32 v[68:69], v[68:69], v[186:187]
	v_pk_mul_f32 v[70:71], v[70:71], v[188:189]
	v_pk_fma_f32 v[68:69], v[160:161], v[68:69], v[210:211]
	v_pk_fma_f32 v[70:71], v[162:163], v[70:71], v[212:213]
	global_store_dwordx4 v142, v[68:71], s[66:67] offset:512 sc1
	s_add_u32 s64, s64, 0x10000
	s_addc_u32 s65, s65, 0
	global_load_dwordx4 v[210:213], v142, s[64:65]
	s_waitcnt vmcnt(18)
	v_pk_mul_f32 v[64:65], v[64:65], v[190:191]
	v_pk_mul_f32 v[66:67], v[66:67], v[192:193]
	v_pk_fma_f32 v[64:65], v[164:165], v[64:65], v[214:215]
	v_pk_fma_f32 v[66:67], v[166:167], v[66:67], v[216:217]
	global_store_dwordx4 v142, v[64:67], s[66:67] offset:576 sc1
	global_load_dwordx4 v[214:217], v142, s[64:65] offset:64
	s_add_u32 s66, s66, 0x50000
	s_addc_u32 s67, s67, 0
	s_waitcnt vmcnt(18)
	v_pk_mul_f32 v[60:61], v[60:61], v[178:179]
	v_pk_mul_f32 v[62:63], v[62:63], v[180:181]
	v_pk_fma_f32 v[60:61], v[152:153], v[60:61], v[218:219]
	v_pk_fma_f32 v[62:63], v[154:155], v[62:63], v[220:221]
	global_store_dwordx4 v142, v[60:63], s[66:67] sc1
	global_load_dwordx4 v[218:221], v142, s[64:65] offset:512
	s_waitcnt vmcnt(18)
	v_pk_mul_f32 v[56:57], v[56:57], v[182:183]
	v_pk_mul_f32 v[58:59], v[58:59], v[184:185]
	v_pk_fma_f32 v[56:57], v[156:157], v[56:57], v[222:223]
	v_pk_fma_f32 v[58:59], v[158:159], v[58:59], v[224:225]
	global_store_dwordx4 v142, v[56:59], s[66:67] offset:64 sc1
	global_load_dwordx4 v[222:225], v142, s[64:65] offset:576
	s_waitcnt vmcnt(18)
	v_pk_mul_f32 v[28:29], v[28:29], v[186:187]
	v_pk_mul_f32 v[30:31], v[30:31], v[188:189]
	v_pk_fma_f32 v[28:29], v[160:161], v[28:29], v[226:227]
	v_pk_fma_f32 v[30:31], v[162:163], v[30:31], v[228:229]
	global_store_dwordx4 v142, v[28:31], s[66:67] offset:512 sc1
	s_add_u32 s64, s64, 0x10000
	s_addc_u32 s65, s65, 0
	global_load_dwordx4 v[226:229], v142, s[64:65]
	s_waitcnt vmcnt(18)
	v_pk_mul_f32 v[24:25], v[24:25], v[190:191]
	v_pk_mul_f32 v[26:27], v[26:27], v[192:193]
	v_pk_fma_f32 v[24:25], v[164:165], v[24:25], v[230:231]
	v_pk_fma_f32 v[26:27], v[166:167], v[26:27], v[232:233]
	global_store_dwordx4 v142, v[24:27], s[66:67] offset:576 sc1
	global_load_dwordx4 v[230:233], v142, s[64:65] offset:64
	s_add_u32 s66, s66, 0x10000
	s_addc_u32 s67, s67, 0
	s_waitcnt vmcnt(18)
	v_pk_mul_f32 v[52:53], v[52:53], v[178:179]
	v_pk_mul_f32 v[54:55], v[54:55], v[180:181]
	v_pk_fma_f32 v[52:53], v[152:153], v[52:53], v[194:195]
	v_pk_fma_f32 v[54:55], v[154:155], v[54:55], v[196:197]
	global_store_dwordx4 v142, v[52:55], s[66:67] sc1
	global_load_dwordx4 v[194:197], v142, s[64:65] offset:512
	s_waitcnt vmcnt(18)
	v_pk_mul_f32 v[48:49], v[48:49], v[182:183]
	v_pk_mul_f32 v[50:51], v[50:51], v[184:185]
	v_pk_fma_f32 v[48:49], v[156:157], v[48:49], v[198:199]
	v_pk_fma_f32 v[50:51], v[158:159], v[50:51], v[200:201]
	global_store_dwordx4 v142, v[48:51], s[66:67] offset:64 sc1
	global_load_dwordx4 v[198:201], v142, s[64:65] offset:576
	s_waitcnt vmcnt(18)
	v_pk_mul_f32 v[20:21], v[20:21], v[186:187]
	v_pk_mul_f32 v[22:23], v[22:23], v[188:189]
	v_pk_fma_f32 v[20:21], v[160:161], v[20:21], v[202:203]
	v_pk_fma_f32 v[22:23], v[162:163], v[22:23], v[204:205]
	global_store_dwordx4 v142, v[20:23], s[66:67] offset:512 sc1
	s_waitcnt vmcnt(17)
	v_pk_mul_f32 v[16:17], v[16:17], v[190:191]
	v_pk_mul_f32 v[18:19], v[18:19], v[192:193]
	v_pk_fma_f32 v[16:17], v[164:165], v[16:17], v[206:207]
	v_pk_fma_f32 v[18:19], v[166:167], v[18:19], v[208:209]
	global_store_dwordx4 v142, v[16:19], s[66:67] offset:576 sc1
	s_add_u32 s66, s66, 0x10000
	s_addc_u32 s67, s67, 0
	s_waitcnt vmcnt(16)
	v_pk_mul_f32 v[44:45], v[44:45], v[178:179]
	v_pk_mul_f32 v[46:47], v[46:47], v[180:181]
	v_pk_fma_f32 v[44:45], v[152:153], v[44:45], v[210:211]
	v_pk_fma_f32 v[46:47], v[154:155], v[46:47], v[212:213]
	global_store_dwordx4 v142, v[44:47], s[66:67] sc1
	s_waitcnt vmcnt(15)
	v_pk_mul_f32 v[40:41], v[40:41], v[182:183]
	v_pk_mul_f32 v[42:43], v[42:43], v[184:185]
	v_pk_fma_f32 v[40:41], v[156:157], v[40:41], v[214:215]
	v_pk_fma_f32 v[42:43], v[158:159], v[42:43], v[216:217]
	global_store_dwordx4 v142, v[40:43], s[66:67] offset:64 sc1
	s_waitcnt vmcnt(14)
	v_pk_mul_f32 v[12:13], v[12:13], v[186:187]
	v_pk_mul_f32 v[14:15], v[14:15], v[188:189]
	v_pk_fma_f32 v[12:13], v[160:161], v[12:13], v[218:219]
	v_pk_fma_f32 v[14:15], v[162:163], v[14:15], v[220:221]
	global_store_dwordx4 v142, v[12:15], s[66:67] offset:512 sc1
	s_waitcnt vmcnt(13)
	v_pk_mul_f32 v[8:9], v[8:9], v[190:191]
	v_pk_mul_f32 v[10:11], v[10:11], v[192:193]
	v_pk_fma_f32 v[8:9], v[164:165], v[8:9], v[222:223]
	v_pk_fma_f32 v[10:11], v[166:167], v[10:11], v[224:225]
	global_store_dwordx4 v142, v[8:11], s[66:67] offset:576 sc1
	s_add_u32 s66, s66, 0x10000
	s_addc_u32 s67, s67, 0
	s_waitcnt vmcnt(12)
	v_pk_mul_f32 v[36:37], v[36:37], v[178:179]
	v_pk_mul_f32 v[38:39], v[38:39], v[180:181]
	v_pk_fma_f32 v[36:37], v[152:153], v[36:37], v[226:227]
	v_pk_fma_f32 v[38:39], v[154:155], v[38:39], v[228:229]
	global_store_dwordx4 v142, v[36:39], s[66:67] sc1
	s_waitcnt vmcnt(11)
	v_pk_mul_f32 v[32:33], v[32:33], v[182:183]
	v_pk_mul_f32 v[34:35], v[34:35], v[184:185]
	v_pk_fma_f32 v[32:33], v[156:157], v[32:33], v[230:231]
	v_pk_fma_f32 v[34:35], v[158:159], v[34:35], v[232:233]
	global_store_dwordx4 v142, v[32:35], s[66:67] offset:64 sc1
	s_waitcnt vmcnt(10)
	v_pk_mul_f32 v[4:5], v[4:5], v[186:187]
	v_pk_mul_f32 v[6:7], v[6:7], v[188:189]
	v_pk_fma_f32 v[4:5], v[160:161], v[4:5], v[194:195]
	v_pk_fma_f32 v[6:7], v[162:163], v[6:7], v[196:197]
	global_store_dwordx4 v142, v[4:7], s[66:67] offset:512 sc1
	s_waitcnt vmcnt(9)
	v_pk_mul_f32 v[0:1], v[0:1], v[190:191]
	v_pk_mul_f32 v[2:3], v[2:3], v[192:193]
	v_pk_fma_f32 v[0:1], v[164:165], v[0:1], v[198:199]
	v_pk_fma_f32 v[2:3], v[166:167], v[2:3], v[200:201]
	global_store_dwordx4 v142, v[0:3], s[66:67] offset:576 sc1
	s_mov_b32 s91, s36
	s_mov_b64 s[54:55], s[52:53]
	s_mov_b64 s[56:57], s[50:51]
	s_mov_b32 s22, s40
	s_and_b64 vcc, exec, s[12:13]
	s_cbranch_vccz .LBB0_1823
	s_branch .LBB0_1832

.LBB0_2049:
	ds_read_b128 v[144:147], v155
	ds_read_b128 v[148:151], v155 offset:1024
	ds_read_b128 v[158:161], v155 offset:2048
	ds_read_b128 v[162:165], v155 offset:3072
	s_add_u32 s33, s40, 0x4000
	s_addc_u32 s48, s41, 0
	s_cmp_eq_u32 s80, 60
	s_cselect_b32 s52, s76, s33
	s_cselect_b32 s53, s31, s48
	s_cselect_b32 s48, s77, s78
	s_cselect_b32 s49, s29, s79
	s_add_u32 s50, s52, 0x8000
	s_addc_u32 s51, s53, 0
	v_lshl_add_u64 v[206:207], s[40:41], 0, v[138:139]
	s_add_i32 m0, s58, 0xc000
	ds_read_b128 v[166:169], v156
	ds_read_b128 v[178:181], v156 offset:1024
	ds_read_b128 v[182:185], v156 offset:2048
	ds_read_b128 v[186:189], v156 offset:3072
	ds_read_b128 v[190:193], v156 offset:4096
	ds_read_b128 v[194:197], v156 offset:5120
	ds_read_b128 v[198:201], v156 offset:6144
	ds_read_b128 v[202:205], v156 offset:7168
	global_load_lds_dwordx4 v[206:207], off
	v_lshl_add_u64 v[206:207], s[40:41], 0, v[136:137]
	s_add_i32 m0, s58, 0xe000
	s_nop 0
	global_load_lds_dwordx4 v[206:207], off
	s_waitcnt lgkmcnt(8)
	s_barrier
	s_waitcnt lgkmcnt(0)
	s_setprio 1
	s_waitcnt lgkmcnt(0)
	v_mfma_f32_16x16x32_bf16 v[124:127], v[144:147], v[166:169], v[124:127]
	v_mfma_f32_16x16x32_bf16 v[120:123], v[158:161], v[166:169], v[120:123]
	v_mfma_f32_16x16x32_bf16 v[108:111], v[144:147], v[182:185], v[108:111]
	v_mfma_f32_16x16x32_bf16 v[104:107], v[158:161], v[182:185], v[104:107]
	v_mfma_f32_16x16x32_bf16 v[92:95], v[144:147], v[190:193], v[92:95]
	v_mfma_f32_16x16x32_bf16 v[88:91], v[158:161], v[190:193], v[88:91]
	v_mfma_f32_16x16x32_bf16 v[76:79], v[144:147], v[198:201], v[76:79]
	v_mfma_f32_16x16x32_bf16 v[72:75], v[158:161], v[198:201], v[72:75]
	v_mfma_f32_16x16x32_bf16 v[124:127], v[148:151], v[178:181], v[124:127]
	v_mfma_f32_16x16x32_bf16 v[120:123], v[162:165], v[178:181], v[120:123]
	v_mfma_f32_16x16x32_bf16 v[108:111], v[148:151], v[186:189], v[108:111]
	v_mfma_f32_16x16x32_bf16 v[104:107], v[162:165], v[186:189], v[104:107]
	v_mfma_f32_16x16x32_bf16 v[92:95], v[148:151], v[194:197], v[92:95]
	v_mfma_f32_16x16x32_bf16 v[88:91], v[162:165], v[194:197], v[88:91]
	v_mfma_f32_16x16x32_bf16 v[76:79], v[148:151], v[202:205], v[76:79]
	v_mfma_f32_16x16x32_bf16 v[72:75], v[162:165], v[202:205], v[72:75]
	s_setprio 0
	s_barrier
	s_add_i32 s33, s68, s57
	v_lshl_add_u64 v[222:223], s[48:49], 0, v[132:133]
	s_mov_b32 m0, s33
	ds_read_b128 v[206:209], v157
	ds_read_b128 v[210:213], v157 offset:1024
	ds_read_b128 v[214:217], v157 offset:2048
	ds_read_b128 v[218:221], v157 offset:3072
	global_load_lds_dwordx4 v[222:223], off
	v_lshl_add_u64 v[224:225], s[48:49], 0, v[128:129]
	s_add_i32 m0, s33, 0x2000
	s_nop 0
	global_load_lds_dwordx4 v[224:225], off
	s_barrier
	s_waitcnt lgkmcnt(0)
	s_setprio 1
	s_waitcnt lgkmcnt(0)
	v_mfma_f32_16x16x32_bf16 v[116:119], v[206:209], v[166:169], v[116:119]
	v_mfma_f32_16x16x32_bf16 v[112:115], v[214:217], v[166:169], v[112:115]
	v_mfma_f32_16x16x32_bf16 v[100:103], v[206:209], v[182:185], v[100:103]
	v_mfma_f32_16x16x32_bf16 v[96:99], v[214:217], v[182:185], v[96:99]
	v_mfma_f32_16x16x32_bf16 v[84:87], v[206:209], v[190:193], v[84:87]
	v_mfma_f32_16x16x32_bf16 v[80:83], v[214:217], v[190:193], v[80:83]
	v_mfma_f32_16x16x32_bf16 v[68:71], v[206:209], v[198:201], v[68:71]
	v_mfma_f32_16x16x32_bf16 v[64:67], v[214:217], v[198:201], v[64:67]
	v_mfma_f32_16x16x32_bf16 v[116:119], v[210:213], v[178:181], v[116:119]
	v_mfma_f32_16x16x32_bf16 v[112:115], v[218:221], v[178:181], v[112:115]
	v_mfma_f32_16x16x32_bf16 v[100:103], v[210:213], v[186:189], v[100:103]
	v_mfma_f32_16x16x32_bf16 v[96:99], v[218:221], v[186:189], v[96:99]
	v_mfma_f32_16x16x32_bf16 v[84:87], v[210:213], v[194:197], v[84:87]
	v_mfma_f32_16x16x32_bf16 v[80:83], v[218:221], v[194:197], v[80:83]
	v_mfma_f32_16x16x32_bf16 v[68:71], v[210:213], v[202:205], v[68:71]
	v_mfma_f32_16x16x32_bf16 v[64:67], v[218:221], v[202:205], v[64:67]
	s_setprio 0
	s_mov_b32 m0, s58
	v_lshl_add_u64 v[226:227], s[52:53], 0, v[134:135]
	s_barrier
	ds_read_b128 v[166:169], v156 offset:16384
	ds_read_b128 v[178:181], v156 offset:17408
	ds_read_b128 v[182:185], v156 offset:18432
	ds_read_b128 v[186:189], v156 offset:19456
	ds_read_b128 v[190:193], v156 offset:20480
	ds_read_b128 v[194:197], v156 offset:21504
	ds_read_b128 v[198:201], v156 offset:22528
	ds_read_b128 v[202:205], v156 offset:23552
	global_load_lds_dwordx4 v[226:227], off
	v_lshl_add_u64 v[226:227], s[52:53], 0, v[130:131]
	s_mov_b32 m0, s59
	s_nop 0
	global_load_lds_dwordx4 v[226:227], off
	s_barrier
	s_waitcnt lgkmcnt(0)
	s_setprio 1
	s_waitcnt lgkmcnt(0)
	v_mfma_f32_16x16x32_bf16 v[60:63], v[144:147], v[166:169], v[60:63]
	v_mfma_f32_16x16x32_bf16 v[56:59], v[158:161], v[166:169], v[56:59]
	v_mfma_f32_16x16x32_bf16 v[44:47], v[144:147], v[182:185], v[44:47]
	v_mfma_f32_16x16x32_bf16 v[40:43], v[158:161], v[182:185], v[40:43]
	v_mfma_f32_16x16x32_bf16 v[28:31], v[144:147], v[190:193], v[28:31]
	v_mfma_f32_16x16x32_bf16 v[24:27], v[158:161], v[190:193], v[24:27]
	v_mfma_f32_16x16x32_bf16 v[12:15], v[144:147], v[198:201], v[12:15]
	v_mfma_f32_16x16x32_bf16 v[8:11], v[158:161], v[198:201], v[8:11]
	v_mfma_f32_16x16x32_bf16 v[60:63], v[148:151], v[178:181], v[60:63]
	v_mfma_f32_16x16x32_bf16 v[56:59], v[162:165], v[178:181], v[56:59]
	v_mfma_f32_16x16x32_bf16 v[44:47], v[148:151], v[186:189], v[44:47]
	v_mfma_f32_16x16x32_bf16 v[40:43], v[162:165], v[186:189], v[40:43]
	v_mfma_f32_16x16x32_bf16 v[28:31], v[148:151], v[194:197], v[28:31]
	v_mfma_f32_16x16x32_bf16 v[24:27], v[162:165], v[194:197], v[24:27]
	v_mfma_f32_16x16x32_bf16 v[12:15], v[148:151], v[202:205], v[12:15]
	v_mfma_f32_16x16x32_bf16 v[8:11], v[162:165], v[202:205], v[8:11]
	s_setprio 0
	s_barrier
	s_add_u32 s82, s48, 0x100000
	s_addc_u32 s83, s49, 0
	s_add_i32 s33, s69, s57
	v_lshl_add_u64 v[144:145], s[82:83], 0, v[132:133]
	s_mov_b32 m0, s33
	s_nop 0
	global_load_lds_dwordx4 v[144:145], off
	v_lshl_add_u64 v[144:145], s[82:83], 0, v[128:129]
	s_add_i32 m0, s33, 0x2000
	s_nop 0
	global_load_lds_dwordx4 v[144:145], off
	s_waitcnt vmcnt(6)
	s_barrier
	s_setprio 1
	v_mfma_f32_16x16x32_bf16 v[52:55], v[206:209], v[166:169], v[52:55]
	v_mfma_f32_16x16x32_bf16 v[48:51], v[214:217], v[166:169], v[48:51]
	v_mfma_f32_16x16x32_bf16 v[36:39], v[206:209], v[182:185], v[36:39]
	v_mfma_f32_16x16x32_bf16 v[32:35], v[214:217], v[182:185], v[32:35]
	v_mfma_f32_16x16x32_bf16 v[20:23], v[206:209], v[190:193], v[20:23]
	v_mfma_f32_16x16x32_bf16 v[16:19], v[214:217], v[190:193], v[16:19]
	v_mfma_f32_16x16x32_bf16 v[4:7], v[206:209], v[198:201], v[4:7]
	v_mfma_f32_16x16x32_bf16 v[0:3], v[214:217], v[198:201], v[0:3]
	v_mfma_f32_16x16x32_bf16 v[52:55], v[210:213], v[178:181], v[52:55]
	v_mfma_f32_16x16x32_bf16 v[48:51], v[218:221], v[178:181], v[48:51]
	v_mfma_f32_16x16x32_bf16 v[36:39], v[210:213], v[186:189], v[36:39]
	v_mfma_f32_16x16x32_bf16 v[32:35], v[218:221], v[186:189], v[32:35]
	v_mfma_f32_16x16x32_bf16 v[20:23], v[210:213], v[194:197], v[20:23]
	v_mfma_f32_16x16x32_bf16 v[16:19], v[218:221], v[194:197], v[16:19]
	v_mfma_f32_16x16x32_bf16 v[4:7], v[210:213], v[202:205], v[4:7]
	v_mfma_f32_16x16x32_bf16 v[0:3], v[218:221], v[202:205], v[0:3]
	s_setprio 0
	s_add_i32 s33, 0, 0x18000
	v_add_u32_e32 v162, s33, v153
	s_barrier
	ds_read_b128 v[144:147], v162
	ds_read_b128 v[148:151], v162 offset:1024
	ds_read_b128 v[158:161], v162 offset:2048
	ds_read_b128 v[162:165], v162 offset:3072
	s_add_u32 s52, s52, 0x4000
	s_addc_u32 s53, s53, 0
	s_mov_b32 m0, s60
	v_lshl_add_u64 v[206:207], s[52:53], 0, v[134:135]
	ds_read_b128 v[166:169], v156 offset:32768
	ds_read_b128 v[178:181], v156 offset:33792
	ds_read_b128 v[182:185], v156 offset:34816
	ds_read_b128 v[186:189], v156 offset:35840
	ds_read_b128 v[190:193], v156 offset:36864
	ds_read_b128 v[194:197], v156 offset:37888
	ds_read_b128 v[198:201], v156 offset:38912
	ds_read_b128 v[202:205], v156 offset:39936
	global_load_lds_dwordx4 v[206:207], off
	v_lshl_add_u64 v[206:207], s[52:53], 0, v[130:131]
	s_mov_b32 m0, s61
	s_nop 0
	global_load_lds_dwordx4 v[206:207], off
	s_waitcnt lgkmcnt(8)
	s_barrier
	s_waitcnt lgkmcnt(0)
	s_setprio 1
	s_waitcnt lgkmcnt(0)
	v_mfma_f32_16x16x32_bf16 v[124:127], v[144:147], v[166:169], v[124:127]
	v_mfma_f32_16x16x32_bf16 v[120:123], v[158:161], v[166:169], v[120:123]
	v_mfma_f32_16x16x32_bf16 v[108:111], v[144:147], v[182:185], v[108:111]
	v_mfma_f32_16x16x32_bf16 v[104:107], v[158:161], v[182:185], v[104:107]
	v_mfma_f32_16x16x32_bf16 v[92:95], v[144:147], v[190:193], v[92:95]
	v_mfma_f32_16x16x32_bf16 v[88:91], v[158:161], v[190:193], v[88:91]
	v_mfma_f32_16x16x32_bf16 v[76:79], v[144:147], v[198:201], v[76:79]
	v_mfma_f32_16x16x32_bf16 v[72:75], v[158:161], v[198:201], v[72:75]
	v_mfma_f32_16x16x32_bf16 v[124:127], v[148:151], v[178:181], v[124:127]
	v_mfma_f32_16x16x32_bf16 v[120:123], v[162:165], v[178:181], v[120:123]
	v_mfma_f32_16x16x32_bf16 v[108:111], v[148:151], v[186:189], v[108:111]
	v_mfma_f32_16x16x32_bf16 v[104:107], v[162:165], v[186:189], v[104:107]
	v_mfma_f32_16x16x32_bf16 v[92:95], v[148:151], v[194:197], v[92:95]
	v_mfma_f32_16x16x32_bf16 v[88:91], v[162:165], v[194:197], v[88:91]
	v_mfma_f32_16x16x32_bf16 v[76:79], v[148:151], v[202:205], v[76:79]
	v_mfma_f32_16x16x32_bf16 v[72:75], v[162:165], v[202:205], v[72:75]
	s_setprio 0
	s_barrier
	s_add_i32 s52, 0, 0x1c000
	s_add_i32 s33, s33, s57
	v_add_u32_e32 v177, s52, v153
	v_lshl_add_u64 v[222:223], v[222:223], 0, s[18:19]
	s_mov_b32 m0, s33
	ds_read_b128 v[206:209], v177
	ds_read_b128 v[210:213], v177 offset:1024
	ds_read_b128 v[214:217], v177 offset:2048
	ds_read_b128 v[218:221], v177 offset:3072
	global_load_lds_dwordx4 v[222:223], off
	v_lshl_add_u64 v[222:223], v[224:225], 0, s[18:19]
	s_add_i32 m0, s33, 0x2000
	s_nop 0
	global_load_lds_dwordx4 v[222:223], off
	s_barrier
	s_waitcnt lgkmcnt(0)
	s_setprio 1
	s_waitcnt lgkmcnt(0)
	v_mfma_f32_16x16x32_bf16 v[116:119], v[206:209], v[166:169], v[116:119]
	v_mfma_f32_16x16x32_bf16 v[112:115], v[214:217], v[166:169], v[112:115]
	v_mfma_f32_16x16x32_bf16 v[100:103], v[206:209], v[182:185], v[100:103]
	v_mfma_f32_16x16x32_bf16 v[96:99], v[214:217], v[182:185], v[96:99]
	v_mfma_f32_16x16x32_bf16 v[84:87], v[206:209], v[190:193], v[84:87]
	v_mfma_f32_16x16x32_bf16 v[80:83], v[214:217], v[190:193], v[80:83]
	v_mfma_f32_16x16x32_bf16 v[68:71], v[206:209], v[198:201], v[68:71]
	v_mfma_f32_16x16x32_bf16 v[64:67], v[214:217], v[198:201], v[64:67]
	v_mfma_f32_16x16x32_bf16 v[116:119], v[210:213], v[178:181], v[116:119]
	v_mfma_f32_16x16x32_bf16 v[112:115], v[218:221], v[178:181], v[112:115]
	v_mfma_f32_16x16x32_bf16 v[100:103], v[210:213], v[186:189], v[100:103]
	v_mfma_f32_16x16x32_bf16 v[96:99], v[218:221], v[186:189], v[96:99]
	v_mfma_f32_16x16x32_bf16 v[84:87], v[210:213], v[194:197], v[84:87]
	v_mfma_f32_16x16x32_bf16 v[80:83], v[218:221], v[194:197], v[80:83]
	v_mfma_f32_16x16x32_bf16 v[68:71], v[210:213], v[202:205], v[68:71]
	v_mfma_f32_16x16x32_bf16 v[64:67], v[218:221], v[202:205], v[64:67]
	s_setprio 0
	s_mov_b32 m0, s62
	v_lshl_add_u64 v[222:223], s[50:51], 0, v[134:135]
	s_barrier
	ds_read_b128 v[166:169], v156 offset:49152
	ds_read_b128 v[178:181], v156 offset:50176
	ds_read_b128 v[182:185], v156 offset:51200
	ds_read_b128 v[186:189], v156 offset:52224
	ds_read_b128 v[190:193], v156 offset:53248
	ds_read_b128 v[194:197], v156 offset:54272
	ds_read_b128 v[198:201], v156 offset:55296
	ds_read_b128 v[202:205], v156 offset:56320
	global_load_lds_dwordx4 v[222:223], off
	v_lshl_add_u64 v[222:223], s[50:51], 0, v[130:131]
	s_mov_b32 m0, s63
	s_nop 0
	global_load_lds_dwordx4 v[222:223], off
	s_barrier
	s_waitcnt lgkmcnt(0)
	s_setprio 1
	s_waitcnt lgkmcnt(0)
	v_mfma_f32_16x16x32_bf16 v[60:63], v[144:147], v[166:169], v[60:63]
	v_mfma_f32_16x16x32_bf16 v[56:59], v[158:161], v[166:169], v[56:59]
	v_mfma_f32_16x16x32_bf16 v[44:47], v[144:147], v[182:185], v[44:47]
	v_mfma_f32_16x16x32_bf16 v[40:43], v[158:161], v[182:185], v[40:43]
	v_mfma_f32_16x16x32_bf16 v[28:31], v[144:147], v[190:193], v[28:31]
	v_mfma_f32_16x16x32_bf16 v[24:27], v[158:161], v[190:193], v[24:27]
	v_mfma_f32_16x16x32_bf16 v[12:15], v[144:147], v[198:201], v[12:15]
	v_mfma_f32_16x16x32_bf16 v[8:11], v[158:161], v[198:201], v[8:11]
	v_mfma_f32_16x16x32_bf16 v[60:63], v[148:151], v[178:181], v[60:63]
	v_mfma_f32_16x16x32_bf16 v[56:59], v[162:165], v[178:181], v[56:59]
	v_mfma_f32_16x16x32_bf16 v[44:47], v[148:151], v[186:189], v[44:47]
	v_mfma_f32_16x16x32_bf16 v[40:43], v[162:165], v[186:189], v[40:43]
	v_mfma_f32_16x16x32_bf16 v[28:31], v[148:151], v[194:197], v[28:31]
	v_mfma_f32_16x16x32_bf16 v[24:27], v[162:165], v[194:197], v[24:27]
	v_mfma_f32_16x16x32_bf16 v[12:15], v[148:151], v[202:205], v[12:15]
	v_mfma_f32_16x16x32_bf16 v[8:11], v[162:165], v[202:205], v[8:11]
	s_setprio 0
	s_barrier
	s_add_u32 s48, s48, 0x100080
	s_addc_u32 s49, s49, 0
	s_add_i32 s33, s52, s57
	v_lshl_add_u64 v[144:145], s[48:49], 0, v[132:133]
	s_mov_b32 m0, s33
	s_nop 0
	global_load_lds_dwordx4 v[144:145], off
	v_lshl_add_u64 v[144:145], s[48:49], 0, v[128:129]
	s_add_i32 m0, s33, 0x2000
	s_nop 0
	global_load_lds_dwordx4 v[144:145], off
	s_waitcnt vmcnt(6)
	s_barrier
	s_setprio 1
	v_mfma_f32_16x16x32_bf16 v[52:55], v[206:209], v[166:169], v[52:55]
	v_mfma_f32_16x16x32_bf16 v[48:51], v[214:217], v[166:169], v[48:51]
	v_mfma_f32_16x16x32_bf16 v[36:39], v[206:209], v[182:185], v[36:39]
	v_mfma_f32_16x16x32_bf16 v[32:35], v[214:217], v[182:185], v[32:35]
	v_mfma_f32_16x16x32_bf16 v[20:23], v[206:209], v[190:193], v[20:23]
	v_mfma_f32_16x16x32_bf16 v[16:19], v[214:217], v[190:193], v[16:19]
	v_mfma_f32_16x16x32_bf16 v[4:7], v[206:209], v[198:201], v[4:7]
	v_mfma_f32_16x16x32_bf16 v[0:3], v[214:217], v[198:201], v[0:3]
	v_mfma_f32_16x16x32_bf16 v[52:55], v[210:213], v[178:181], v[52:55]
	v_mfma_f32_16x16x32_bf16 v[48:51], v[218:221], v[178:181], v[48:51]
	v_mfma_f32_16x16x32_bf16 v[36:39], v[210:213], v[186:189], v[36:39]
	v_mfma_f32_16x16x32_bf16 v[32:35], v[218:221], v[186:189], v[32:35]
	v_mfma_f32_16x16x32_bf16 v[20:23], v[210:213], v[194:197], v[20:23]
	v_mfma_f32_16x16x32_bf16 v[16:19], v[218:221], v[194:197], v[16:19]
	v_mfma_f32_16x16x32_bf16 v[4:7], v[210:213], v[202:205], v[4:7]
	v_mfma_f32_16x16x32_bf16 v[0:3], v[218:221], v[202:205], v[0:3]
	s_setprio 0
	s_add_i32 s80, s80, 2
	s_add_u32 s78, s78, 0x100
	s_addc_u32 s79, s79, 0
	s_add_u32 s40, s40, 0x10000
	s_addc_u32 s41, s41, 0
	s_cmp_gt_u32 s80, 61
	s_barrier
	s_cbranch_scc0 .LBB0_2049
	s_lshl_b32 s82, s10, 8
	v_lshl_or_b32 v145, s75, 8, v154
	v_add_u32_e32 v144, s82, v152
	v_lshlrev_b32_e32 v145, 2, v145
	s_sub_u32 s83, s82, 0x1000
	s_lshr_b32 s83, s83, 11
	s_mul_i32 s83, s83, 6
	s_add_i32 s83, s83, 41
	s_cmp_gt_i32 s10, 15
	s_cselect_b32 s83, s83, 35
	s_lshl_b32 s83, s83, 12
	s_add_u32 s50, s66, s83
	s_addc_u32 s51, s67, 0
	v_lshl_add_u32 v146, v144, 12, v145
	global_load_dwordx4 v[148:151], v145, s[50:51]
	global_load_dwordx4 v[158:161], v145, s[50:51] offset:64
	global_load_dwordx4 v[162:165], v145, s[50:51] offset:512
	global_load_dwordx4 v[166:169], v145, s[50:51] offset:576
	s_mov_b64 s[84:85], s[12:13]
	s_mov_b64 s[86:87], s[12:13]
	global_load_dwordx4 v[178:181], v146, s[84:85]
	global_load_dwordx4 v[182:185], v146, s[84:85] offset:64
	global_load_dwordx4 v[186:189], v146, s[84:85] offset:512
	global_load_dwordx4 v[190:193], v146, s[84:85] offset:576
	s_add_u32 s84, s84, 0x10000
	s_addc_u32 s85, s85, 0
	global_load_dwordx4 v[194:197], v146, s[84:85]
	global_load_dwordx4 v[198:201], v146, s[84:85] offset:64
	global_load_dwordx4 v[202:205], v146, s[84:85] offset:512
	global_load_dwordx4 v[206:209], v146, s[84:85] offset:576
	s_add_u32 s84, s84, 0x10000
	s_addc_u32 s85, s85, 0
	global_load_dwordx4 v[210:213], v146, s[84:85]
	global_load_dwordx4 v[214:217], v146, s[84:85] offset:64
	global_load_dwordx4 v[218:221], v146, s[84:85] offset:512
	global_load_dwordx4 v[222:225], v146, s[84:85] offset:576
	s_add_u32 s84, s84, 0x10000
	s_addc_u32 s85, s85, 0
	global_load_dwordx4 v[226:229], v146, s[84:85]
	global_load_dwordx4 v[230:233], v146, s[84:85] offset:64
	s_waitcnt vmcnt(13)
	v_pk_fma_f32 v[124:125], v[124:125], v[148:149], v[178:179]
	v_pk_fma_f32 v[126:127], v[126:127], v[150:151], v[180:181]
	global_store_dwordx4 v146, v[124:127], s[86:87] sc1
	global_load_dwordx4 v[178:181], v146, s[84:85] offset:512
	s_waitcnt vmcnt(14)
	v_pk_fma_f32 v[120:121], v[120:121], v[158:159], v[182:183]
	v_pk_fma_f32 v[122:123], v[122:123], v[160:161], v[184:185]
	global_store_dwordx4 v146, v[120:123], s[86:87] offset:64 sc1
	global_load_dwordx4 v[182:185], v146, s[84:85] offset:576
	s_waitcnt vmcnt(15)
	v_pk_fma_f32 v[116:117], v[116:117], v[162:163], v[186:187]
	v_pk_fma_f32 v[118:119], v[118:119], v[164:165], v[188:189]
	global_store_dwordx4 v146, v[116:119], s[86:87] offset:512 sc1
	s_add_u32 s84, s84, 0x50000
	s_addc_u32 s85, s85, 0
	global_load_dwordx4 v[186:189], v146, s[84:85]
	s_waitcnt vmcnt(16)
	v_pk_fma_f32 v[112:113], v[112:113], v[166:167], v[190:191]
	v_pk_fma_f32 v[114:115], v[114:115], v[168:169], v[192:193]
	global_store_dwordx4 v146, v[112:115], s[86:87] offset:576 sc1
	global_load_dwordx4 v[190:193], v146, s[84:85] offset:64
	s_add_u32 s86, s86, 0x10000
	s_addc_u32 s87, s87, 0
	s_waitcnt vmcnt(17)
	v_pk_fma_f32 v[108:109], v[108:109], v[148:149], v[194:195]
	v_pk_fma_f32 v[110:111], v[110:111], v[150:151], v[196:197]
	global_store_dwordx4 v146, v[108:111], s[86:87] sc1
	global_load_dwordx4 v[194:197], v146, s[84:85] offset:512
	s_waitcnt vmcnt(18)
	v_pk_fma_f32 v[104:105], v[104:105], v[158:159], v[198:199]
	v_pk_fma_f32 v[106:107], v[106:107], v[160:161], v[200:201]
	global_store_dwordx4 v146, v[104:107], s[86:87] offset:64 sc1
	global_load_dwordx4 v[198:201], v146, s[84:85] offset:576
	s_waitcnt vmcnt(19)
	v_pk_fma_f32 v[100:101], v[100:101], v[162:163], v[202:203]
	v_pk_fma_f32 v[102:103], v[102:103], v[164:165], v[204:205]
	global_store_dwordx4 v146, v[100:103], s[86:87] offset:512 sc1
	s_add_u32 s84, s84, 0x10000
	s_addc_u32 s85, s85, 0
	global_load_dwordx4 v[202:205], v146, s[84:85]
	s_waitcnt vmcnt(20)
	v_pk_fma_f32 v[96:97], v[96:97], v[166:167], v[206:207]
	v_pk_fma_f32 v[98:99], v[98:99], v[168:169], v[208:209]
	global_store_dwordx4 v146, v[96:99], s[86:87] offset:576 sc1
	global_load_dwordx4 v[206:209], v146, s[84:85] offset:64
	s_add_u32 s86, s86, 0x10000
	s_addc_u32 s87, s87, 0
	s_waitcnt vmcnt(21)
	v_pk_fma_f32 v[92:93], v[92:93], v[148:149], v[210:211]
	v_pk_fma_f32 v[94:95], v[94:95], v[150:151], v[212:213]
	global_store_dwordx4 v146, v[92:95], s[86:87] sc1
	global_load_dwordx4 v[210:213], v146, s[84:85] offset:512
	s_waitcnt vmcnt(22)
	v_pk_fma_f32 v[88:89], v[88:89], v[158:159], v[214:215]
	v_pk_fma_f32 v[90:91], v[90:91], v[160:161], v[216:217]
	global_store_dwordx4 v146, v[88:91], s[86:87] offset:64 sc1
	global_load_dwordx4 v[214:217], v146, s[84:85] offset:576
	s_waitcnt vmcnt(23)
	v_pk_fma_f32 v[84:85], v[84:85], v[162:163], v[218:219]
	v_pk_fma_f32 v[86:87], v[86:87], v[164:165], v[220:221]
	global_store_dwordx4 v146, v[84:87], s[86:87] offset:512 sc1
	s_add_u32 s84, s84, 0x10000
	s_addc_u32 s85, s85, 0
	global_load_dwordx4 v[218:221], v146, s[84:85]
	s_waitcnt vmcnt(24)
	v_pk_fma_f32 v[80:81], v[80:81], v[166:167], v[222:223]
	v_pk_fma_f32 v[82:83], v[82:83], v[168:169], v[224:225]
	global_store_dwordx4 v146, v[80:83], s[86:87] offset:576 sc1
	global_load_dwordx4 v[222:225], v146, s[84:85] offset:64
	s_add_u32 s86, s86, 0x10000
	s_addc_u32 s87, s87, 0
	s_waitcnt vmcnt(25)
	v_pk_fma_f32 v[76:77], v[76:77], v[148:149], v[226:227]
	v_pk_fma_f32 v[78:79], v[78:79], v[150:151], v[228:229]
	global_store_dwordx4 v146, v[76:79], s[86:87] sc1
	global_load_dwordx4 v[226:229], v146, s[84:85] offset:512
	s_waitcnt vmcnt(26)
	v_pk_fma_f32 v[72:73], v[72:73], v[158:159], v[230:231]
	v_pk_fma_f32 v[74:75], v[74:75], v[160:161], v[232:233]
	global_store_dwordx4 v146, v[72:75], s[86:87] offset:64 sc1
	global_load_dwordx4 v[230:233], v146, s[84:85] offset:576
	s_waitcnt vmcnt(26)
	v_pk_fma_f32 v[68:69], v[68:69], v[162:163], v[178:179]
	v_pk_fma_f32 v[70:71], v[70:71], v[164:165], v[180:181]
	global_store_dwordx4 v146, v[68:71], s[86:87] offset:512 sc1
	s_add_u32 s84, s84, 0x10000
	s_addc_u32 s85, s85, 0
	global_load_dwordx4 v[178:181], v146, s[84:85]
	s_waitcnt vmcnt(26)
	v_pk_fma_f32 v[64:65], v[64:65], v[166:167], v[182:183]
	v_pk_fma_f32 v[66:67], v[66:67], v[168:169], v[184:185]
	global_store_dwordx4 v146, v[64:67], s[86:87] offset:576 sc1
	global_load_dwordx4 v[182:185], v146, s[84:85] offset:64
	s_add_u32 s86, s86, 0x50000
	s_addc_u32 s87, s87, 0
	s_waitcnt vmcnt(26)
	v_pk_fma_f32 v[60:61], v[60:61], v[148:149], v[186:187]
	v_pk_fma_f32 v[62:63], v[62:63], v[150:151], v[188:189]
	global_store_dwordx4 v146, v[60:63], s[86:87] sc1
	global_load_dwordx4 v[186:189], v146, s[84:85] offset:512
	s_waitcnt vmcnt(26)
	v_pk_fma_f32 v[56:57], v[56:57], v[158:159], v[190:191]
	v_pk_fma_f32 v[58:59], v[58:59], v[160:161], v[192:193]
	global_store_dwordx4 v146, v[56:59], s[86:87] offset:64 sc1
	global_load_dwordx4 v[190:193], v146, s[84:85] offset:576
	s_waitcnt vmcnt(26)
	v_pk_fma_f32 v[52:53], v[52:53], v[162:163], v[194:195]
	v_pk_fma_f32 v[54:55], v[54:55], v[164:165], v[196:197]
	global_store_dwordx4 v146, v[52:55], s[86:87] offset:512 sc1
	s_waitcnt vmcnt(25)
	v_pk_fma_f32 v[48:49], v[48:49], v[166:167], v[198:199]
	v_pk_fma_f32 v[50:51], v[50:51], v[168:169], v[200:201]
	global_store_dwordx4 v146, v[48:51], s[86:87] offset:576 sc1
	s_add_u32 s86, s86, 0x10000
	s_addc_u32 s87, s87, 0
	s_waitcnt vmcnt(24)
	v_pk_fma_f32 v[44:45], v[44:45], v[148:149], v[202:203]
	v_pk_fma_f32 v[46:47], v[46:47], v[150:151], v[204:205]
	global_store_dwordx4 v146, v[44:47], s[86:87] sc1
	s_waitcnt vmcnt(23)
	v_pk_fma_f32 v[40:41], v[40:41], v[158:159], v[206:207]
	v_pk_fma_f32 v[42:43], v[42:43], v[160:161], v[208:209]
	global_store_dwordx4 v146, v[40:43], s[86:87] offset:64 sc1
	s_waitcnt vmcnt(22)
	v_pk_fma_f32 v[36:37], v[36:37], v[162:163], v[210:211]
	v_pk_fma_f32 v[38:39], v[38:39], v[164:165], v[212:213]
	global_store_dwordx4 v146, v[36:39], s[86:87] offset:512 sc1
	s_waitcnt vmcnt(21)
	v_pk_fma_f32 v[32:33], v[32:33], v[166:167], v[214:215]
	v_pk_fma_f32 v[34:35], v[34:35], v[168:169], v[216:217]
	global_store_dwordx4 v146, v[32:35], s[86:87] offset:576 sc1
	s_add_u32 s86, s86, 0x10000
	s_addc_u32 s87, s87, 0
	s_waitcnt vmcnt(20)
	v_pk_fma_f32 v[28:29], v[28:29], v[148:149], v[218:219]
	v_pk_fma_f32 v[30:31], v[30:31], v[150:151], v[220:221]
	global_store_dwordx4 v146, v[28:31], s[86:87] sc1
	s_waitcnt vmcnt(19)
	v_pk_fma_f32 v[24:25], v[24:25], v[158:159], v[222:223]
	v_pk_fma_f32 v[26:27], v[26:27], v[160:161], v[224:225]
	global_store_dwordx4 v146, v[24:27], s[86:87] offset:64 sc1
	s_waitcnt vmcnt(18)
	v_pk_fma_f32 v[20:21], v[20:21], v[162:163], v[226:227]
	v_pk_fma_f32 v[22:23], v[22:23], v[164:165], v[228:229]
	global_store_dwordx4 v146, v[20:23], s[86:87] offset:512 sc1
	s_waitcnt vmcnt(17)
	v_pk_fma_f32 v[16:17], v[16:17], v[166:167], v[230:231]
	v_pk_fma_f32 v[18:19], v[18:19], v[168:169], v[232:233]
	global_store_dwordx4 v146, v[16:19], s[86:87] offset:576 sc1
	s_add_u32 s86, s86, 0x10000
	s_addc_u32 s87, s87, 0
	s_waitcnt vmcnt(16)
	v_pk_fma_f32 v[12:13], v[12:13], v[148:149], v[178:179]
	v_pk_fma_f32 v[14:15], v[14:15], v[150:151], v[180:181]
	global_store_dwordx4 v146, v[12:15], s[86:87] sc1
	s_waitcnt vmcnt(15)
	v_pk_fma_f32 v[8:9], v[8:9], v[158:159], v[182:183]
	v_pk_fma_f32 v[10:11], v[10:11], v[160:161], v[184:185]
	global_store_dwordx4 v146, v[8:11], s[86:87] offset:64 sc1
	s_waitcnt vmcnt(14)
	v_pk_fma_f32 v[4:5], v[4:5], v[162:163], v[186:187]
	v_pk_fma_f32 v[6:7], v[6:7], v[164:165], v[188:189]
	global_store_dwordx4 v146, v[4:7], s[86:87] offset:512 sc1
	s_waitcnt vmcnt(13)
	v_pk_fma_f32 v[0:1], v[0:1], v[166:167], v[190:191]
	v_pk_fma_f32 v[2:3], v[2:3], v[168:169], v[192:193]
	global_store_dwordx4 v146, v[0:3], s[86:87] offset:576 sc1
	s_mov_b32 s75, s28
	s_mov_b64 s[40:41], s[36:37]
	s_mov_b64 s[48:49], s[34:35]
	s_mov_b32 s10, s30
	s_and_b64 vcc, exec, s[8:9]
	s_cbranch_vccz .LBB0_2046
	s_waitcnt vmcnt(0)
	s_cmpk_gt_u32 s45, 0xff
	s_cbranch_scc1 .LBB0_2053
	s_barrier
